# prep token loop: 1+(a-1)*ka computed as a*ka+(1-ka) with (1-ka) kept per pass (4 fewer VALU ops per token)
# speedup vs baseline: 1.0108x; 1.0000x over previous
.LBB0_485:
	s_or_b64 exec, exec, s[6:7]
	v_lshl_add_u32 v0, s0, 8, v32
	v_readlane_b32 s60, v253, 46
	v_ashrrev_i32_e32 v1, 31, v0
	v_readlane_b32 s61, v253, 47
	v_readlane_b32 s62, v253, 48
	v_readlane_b32 s63, v253, 49
	v_readlane_b32 s64, v253, 50
	v_readlane_b32 s65, v253, 51
	v_readlane_b32 s66, v253, 52
	v_readlane_b32 s67, v253, 53
	v_lshlrev_b64 v[2:3], 2, v[0:1]
	v_readlane_b32 s52, v253, 62
	v_lshl_add_u32 v0, s0, 9, v0
	v_readlane_b32 s70, v253, 56
	v_readlane_b32 s71, v253, 57
	v_readlane_b32 s74, v253, 60
	v_readlane_b32 s75, v253, 61
	v_readlane_b32 s54, v254, 0
	v_readlane_b32 s55, v254, 1
	v_ashrrev_i32_e32 v1, 31, v0
	v_lshl_add_u64 v[4:5], s[74:75], 0, v[2:3]
	v_lshl_add_u64 v[2:3], s[54:55], 0, v[2:3]
	s_mul_i32 s1, s0, 0x300
	v_lshl_add_u64 v[0:1], v[0:1], 2, s[70:71]
	v_readfirstlane_b32 s82, v160
	s_lshr_b32 s82, s82, 6
	s_lshl_b32 s82, s82, 10
	s_add_i32 s82, s82, 0xd000
	v_add_u32_e32 v249, s82, v251
	ds_write_b128 v249, v[222:225]
	s_waitcnt lgkmcnt(0)
	s_barrier
	s_xor_b64 s[18:19], s[16:17], -1
	v_readlane_b32 s22, v254, 34
	v_readlane_b32 s72, v254, 43
	v_readlane_b32 s73, v254, 44
	v_readlane_b32 s92, v254, 49
	v_readfirstlane_b32 s0, v160
	s_lshr_b32 s0, s0, 6
	s_and_b32 s0, s0, 3
	s_mul_i32 s53, s51, 20
	s_add_i32 s53, s53, s0
	s_lshl_b32 s0, s0, 10
	s_add_i32 s92, s92, s0
	v_and_b32_e32 v250, 63, v160
	v_lshlrev_b32_e32 v251, 4, v250
	v_lshlrev_b32_e32 v250, 3, v250
	v_add_u32_e32 v31, s92, v251
	s_add_u32 s28, s72, 0x664a000
	s_addc_u32 s29, s73, 0
	s_add_u32 s34, s72, 0xaeca000
	s_addc_u32 s35, s73, 0
	s_add_u32 s42, s72, 0x13aca000
	s_addc_u32 s43, s73, 0
	s_waitcnt lgkmcnt(0)
	s_cmp_eq_u64 s[16:17], 0
	s_cbranch_scc1 .Lprep_tok_d1
	ds_read_b128 v[210:213], v251 offset:53248
	ds_read_b128 v[214:217], v251 offset:54272
	ds_read_b128 v[218:221], v251 offset:55296
	ds_read_b128 v[198:201], v251 offset:56320
	ds_read_b128 v[194:197], v251 offset:57344
	ds_read_b128 v[190:193], v251 offset:58368
	ds_read_b128 v[202:205], v251 offset:59392
	ds_read_b128 v[206:209], v251 offset:60416
	s_add_i32 s56, s53, 0
	s_cmpk_lt_i32 s56, 0x2000
	s_movk_i32 s0, 0x3ff
	s_cselect_b32 s0, 0xff, s0
	s_and_b32 s1, s56, s0
	s_cmp_lg_u32 s1, 0
	s_cselect_b32 s59, 1.0, 0
	s_cselect_b32 s1, -1, 0
	s_add_i32 s1, s56, s1
	s_mul_i32 s0, s56, 0x1d00
	s_add_u32 s76, s28, s0
	s_addc_u32 s77, s29, 0
	s_mul_i32 s0, s1, 0x1d00
	s_add_u32 s78, s28, s0
	s_addc_u32 s79, s29, 0
	global_load_dwordx2 v[222:223], v250, s[76:77] offset:0
	global_load_dwordx2 v[224:225], v250, s[76:77] offset:512
	global_load_dwordx2 v[226:227], v250, s[76:77] offset:1024
	global_load_dwordx2 v[228:229], v250, s[78:79] offset:0
	global_load_dwordx2 v[230:231], v250, s[78:79] offset:512
	global_load_dwordx2 v[232:233], v250, s[78:79] offset:1024
	s_add_i32 s57, s53, 4
	s_cmpk_lt_i32 s57, 0x2000
	s_movk_i32 s0, 0x3ff
	s_cselect_b32 s0, 0xff, s0
	s_and_b32 s1, s57, s0
	s_cmp_lg_u32 s1, 0
	s_cselect_b32 s60, 1.0, 0
	s_cselect_b32 s1, -1, 0
	s_add_i32 s1, s57, s1
	s_mul_i32 s0, s57, 0x1d00
	s_add_u32 s80, s28, s0
	s_addc_u32 s81, s29, 0
	s_mul_i32 s0, s1, 0x1d00
	s_add_u32 s82, s28, s0
	s_addc_u32 s83, s29, 0
	global_load_dwordx2 v[236:237], v250, s[80:81] offset:0
	global_load_dwordx2 v[238:239], v250, s[80:81] offset:512
	global_load_dwordx2 v[240:241], v250, s[80:81] offset:1024
	global_load_dwordx2 v[242:243], v250, s[82:83] offset:0
	global_load_dwordx2 v[244:245], v250, s[82:83] offset:512
	global_load_dwordx2 v[246:247], v250, s[82:83] offset:1024
	s_add_i32 s58, s53, 8
	s_cmpk_lt_i32 s58, 0x2000
	s_movk_i32 s0, 0x3ff
	s_cselect_b32 s0, 0xff, s0
	s_and_b32 s1, s58, s0
	s_cmp_lg_u32 s1, 0
	s_cselect_b32 s61, 1.0, 0
	s_cselect_b32 s1, -1, 0
	s_add_i32 s1, s58, s1
	s_mul_i32 s0, s58, 0x1d00
	s_add_u32 s84, s28, s0
	s_addc_u32 s85, s29, 0
	s_mul_i32 s0, s1, 0x1d00
	s_add_u32 s96, s28, s0
	s_addc_u32 s97, s29, 0
	global_load_dwordx2 v[0:1], v250, s[84:85] offset:0
	global_load_dwordx2 v[2:3], v250, s[84:85] offset:512
	global_load_dwordx2 v[4:5], v250, s[84:85] offset:1024
	global_load_dwordx2 v[6:7], v250, s[96:97] offset:0
	global_load_dwordx2 v[8:9], v250, s[96:97] offset:512
	global_load_dwordx2 v[10:11], v250, s[96:97] offset:1024
	ds_read_b128 v[14:17], v31 offset:0
	ds_read_b128 v[18:21], v31 offset:20480
	ds_read_b128 v[22:25], v31 offset:4096
	ds_read_b128 v[26:29], v31 offset:24576
	s_waitcnt lgkmcnt(4)
	s_waitcnt vmcnt(12)
	v_lshlrev_b32_e32 v134, 16, v222
	v_and_b32_e32 v222, 0xffff0000, v222
	v_lshlrev_b32_e32 v135, 16, v223
	v_and_b32_e32 v223, 0xffff0000, v223
	v_lshlrev_b32_e32 v136, 16, v224
	v_and_b32_e32 v224, 0xffff0000, v224
	v_lshlrev_b32_e32 v137, 16, v225
	v_and_b32_e32 v225, 0xffff0000, v225
	v_lshlrev_b32_e32 v138, 16, v226
	v_and_b32_e32 v226, 0xffff0000, v226
	v_lshlrev_b32_e32 v139, 16, v227
	v_and_b32_e32 v227, 0xffff0000, v227
	v_lshlrev_b32_e32 v140, 16, v228
	v_and_b32_e32 v228, 0xffff0000, v228
	v_lshlrev_b32_e32 v141, 16, v229
	v_and_b32_e32 v229, 0xffff0000, v229
	v_lshlrev_b32_e32 v142, 16, v230
	v_and_b32_e32 v230, 0xffff0000, v230
	v_lshlrev_b32_e32 v143, 16, v231
	v_and_b32_e32 v231, 0xffff0000, v231
	v_lshlrev_b32_e32 v144, 16, v232
	v_and_b32_e32 v232, 0xffff0000, v232
	v_lshlrev_b32_e32 v145, 16, v233
	v_and_b32_e32 v233, 0xffff0000, v233
	v_fma_f32 v140, s59, v140, -v134
	v_fma_f32 v228, s59, v228, -v222
	v_fma_f32 v141, s59, v141, -v135
	v_fma_f32 v229, s59, v229, -v223
	v_fmac_f32_e32 v134, v210, v140
	v_fmac_f32_e32 v222, v211, v228
	v_fmac_f32_e32 v135, v212, v141
	v_fmac_f32_e32 v223, v213, v229
	v_fma_f32 v142, s59, v142, -v136
	v_fma_f32 v230, s59, v230, -v224
	v_fma_f32 v143, s59, v143, -v137
	v_fma_f32 v231, s59, v231, -v225
	v_fmac_f32_e32 v136, v214, v142
	v_fmac_f32_e32 v224, v215, v230
	v_fmac_f32_e32 v137, v216, v143
	v_fmac_f32_e32 v225, v217, v231
	v_fma_f32 v144, s59, v144, -v138
	v_fma_f32 v232, s59, v232, -v226
	v_fma_f32 v145, s59, v145, -v139
	v_fma_f32 v233, s59, v233, -v227
	v_fmac_f32_e32 v138, v218, v144
	v_fmac_f32_e32 v226, v219, v232
	v_fmac_f32_e32 v139, v220, v145
	v_fmac_f32_e32 v227, v221, v233
	v_mul_f32_e32 v148, v198, v136
	v_mul_f32_e32 v149, v199, v224
	v_mul_f32_e32 v150, v200, v137
	v_mul_f32_e32 v151, v201, v225
	v_mul_f32_e32 v176, v148, v148
	v_fmac_f32_e32 v176, v149, v149
	v_fmac_f32_e32 v176, v150, v150
	v_fmac_f32_e32 v176, v151, v151
	s_waitcnt lgkmcnt(2)
	v_mul_f32_e32 v194, 0xbfb8aa3b, v194
	v_mul_f32_e32 v195, 0xbfb8aa3b, v195
	v_mul_f32_e32 v196, 0xbfb8aa3b, v196
	v_mul_f32_e32 v197, 0xbfb8aa3b, v197
	v_mul_f32_e32 v190, 0xbfb8aa3b, v190
	v_mul_f32_e32 v191, 0xbfb8aa3b, v191
	v_mul_f32_e32 v192, 0xbfb8aa3b, v192
	v_mul_f32_e32 v193, 0xbfb8aa3b, v193
	v_sub_f32_e32 v33, 1.0, v202
	v_sub_f32_e32 v34, 1.0, v203
	v_sub_f32_e32 v35, 1.0, v204
	v_sub_f32_e32 v36, 1.0, v205
	v_fmamk_f32 v18, v18, 0xbfb8aa3b, v194
	v_fmamk_f32 v19, v19, 0xbfb8aa3b, v195
	v_fmamk_f32 v20, v20, 0xbfb8aa3b, v196
	v_fmamk_f32 v21, v21, 0xbfb8aa3b, v197
	v_add_f32_dpp v176, v176, v176 quad_perm:[1,0,3,2] row_mask:0xf bank_mask:0xf bound_ctrl:1
	v_exp_f32_e32 v18, v18
	v_exp_f32_e32 v19, v19
	v_exp_f32_e32 v20, v20
	v_exp_f32_e32 v21, v21
	v_add_f32_dpp v176, v176, v176 quad_perm:[2,3,0,1] row_mask:0xf bank_mask:0xf bound_ctrl:1
	v_add_f32_e32 v18, 1.0, v18
	v_add_f32_e32 v19, 1.0, v19
	v_add_f32_e32 v20, 1.0, v20
	v_add_f32_e32 v21, 1.0, v21
	v_add_f32_dpp v176, v176, v176 row_half_mirror row_mask:0xf bank_mask:0xf bound_ctrl:1
	v_rcp_f32_e32 v18, v18
	v_rcp_f32_e32 v19, v19
	v_rcp_f32_e32 v20, v20
	v_rcp_f32_e32 v21, v21
	v_add_f32_dpp v176, v176, v176 row_mirror row_mask:0xf bank_mask:0xf bound_ctrl:1
	v_fmamk_f32 v14, v14, 0xbfb8aa3b, v190
	v_fmamk_f32 v15, v15, 0xbfb8aa3b, v191
	v_fmamk_f32 v16, v16, 0xbfb8aa3b, v192
	v_fmamk_f32 v17, v17, 0xbfb8aa3b, v193
	v_sqrt_f32_e32 v176, v176
	v_exp_f32_e32 v14, v14
	v_exp_f32_e32 v15, v15
	v_exp_f32_e32 v16, v16
	v_exp_f32_e32 v17, v17
	v_max_f32_e32 v176, 0x2b8cbccc, v176
	v_add_f32_e32 v14, 1.0, v14
	v_add_f32_e32 v15, 1.0, v15
	v_add_f32_e32 v16, 1.0, v16
	v_add_f32_e32 v17, 1.0, v17
	v_rcp_f32_e32 v178, v176
	v_rcp_f32_e32 v14, v14
	v_rcp_f32_e32 v15, v15
	v_rcp_f32_e32 v16, v16
	v_rcp_f32_e32 v17, v17
	v_mul_f32_e32 v14, 0xbf60028a, v14
	v_mul_f32_e32 v15, 0xbf60028a, v15
	v_mul_f32_e32 v16, 0xbf60028a, v16
	v_mul_f32_e32 v17, 0xbf60028a, v17
	v_exp_f32_e32 v14, v14
	v_exp_f32_e32 v15, v15
	v_exp_f32_e32 v16, v16
	v_exp_f32_e32 v17, v17
	v_fma_f32 v152, v18, v202, v33
	v_fma_f32 v153, v19, v203, v34
	v_fma_f32 v154, v20, v204, v35
	v_fma_f32 v155, v21, v205, v36
	v_mul_f32_e32 v152, v136, v152
	v_mul_f32_e32 v153, v224, v153
	v_mul_f32_e32 v154, v137, v154
	v_mul_f32_e32 v155, v225, v155
	v_mul_f32_e32 v156, v134, v152
	v_mul_f32_e32 v157, v222, v153
	v_mul_f32_e32 v158, v135, v154
	v_mul_f32_e32 v159, v223, v155
	v_mul_f32_e32 v177, v206, v156
	v_fmac_f32_e32 v177, v207, v157
	v_fmac_f32_e32 v177, v208, v158
	v_fmac_f32_e32 v177, v209, v159
	v_mul_f32_e32 v148, v148, v178
	v_mul_f32_e32 v149, v149, v178
	v_add_f32_dpp v177, v177, v177 quad_perm:[1,0,3,2] row_mask:0xf bank_mask:0xf bound_ctrl:1
	v_mul_f32_e32 v150, v150, v178
	v_mul_f32_e32 v151, v151, v178
	v_add_f32_dpp v177, v177, v177 quad_perm:[2,3,0,1] row_mask:0xf bank_mask:0xf bound_ctrl:1
	v_mul_f32_e32 v18, v18, v148
	v_mul_f32_e32 v19, v19, v149
	v_add_f32_dpp v177, v177, v177 row_half_mirror row_mask:0xf bank_mask:0xf bound_ctrl:1
	v_mul_f32_e32 v20, v20, v150
	v_mul_f32_e32 v21, v21, v151
	v_add_f32_dpp v177, v177, v177 row_mirror row_mask:0xf bank_mask:0xf bound_ctrl:1
	s_lshl_b32 s0, s56, 9
	s_add_u32 s62, s34, s0
	s_addc_u32 s63, s35, 0
	v_mul_f32_e32 v156, v138, v177
	v_mul_f32_e32 v157, v226, v177
	v_mul_f32_e32 v158, v139, v177
	v_mul_f32_e32 v159, v227, v177
	v_cvt_pk_bf16_f32 v72, v134, v222
	v_cvt_pk_bf16_f32 v73, v135, v223
	global_store_dwordx2 v250, v[72:73], s[62:63]
	v_cvt_pk_bf16_f32 v74, v14, v15
	v_cvt_pk_bf16_f32 v75, v16, v17
	s_add_u32 s0, s62, 0x500000
	s_addc_u32 s1, s63, 0
	global_store_dwordx2 v250, v[74:75], s[0:1]
	v_cvt_pk_bf16_f32 v180, v152, v153
	v_cvt_pk_bf16_f32 v181, v154, v155
	s_add_u32 s0, s62, 0xa00000
	s_addc_u32 s1, s63, 0
	global_store_dwordx2 v250, v[180:181], s[0:1]
	v_cvt_pk_bf16_f32 v72, v138, v226
	v_cvt_pk_bf16_f32 v73, v139, v227
	s_add_u32 s0, s62, 0xf00000
	s_addc_u32 s1, s63, 0
	global_store_dwordx2 v250, v[72:73], s[0:1]
	v_cvt_pk_bf16_f32 v74, v148, v149
	v_cvt_pk_bf16_f32 v75, v150, v151
	s_add_u32 s0, s62, 0x1400000
	s_addc_u32 s1, s63, 0
	global_store_dwordx2 v250, v[74:75], s[0:1]
	v_cvt_pk_bf16_f32 v180, v18, v19
	v_cvt_pk_bf16_f32 v181, v20, v21
	s_add_u32 s0, s62, 0x1900000
	s_addc_u32 s1, s63, 0
	global_store_dwordx2 v250, v[180:181], s[0:1]
	v_cvt_pk_bf16_f32 v72, v156, v157
	v_cvt_pk_bf16_f32 v73, v158, v159
	s_lshl_b32 s0, s56, 9
	s_add_u32 s0, s42, s0
	s_addc_u32 s1, s43, 0
	global_store_dwordx2 v250, v[72:73], s[0:1]
	s_add_i32 s56, s53, 12
	s_cmpk_lt_i32 s56, 0x2000
	s_movk_i32 s0, 0x3ff
	s_cselect_b32 s0, 0xff, s0
	s_and_b32 s1, s56, s0
	s_cmp_lg_u32 s1, 0
	s_cselect_b32 s59, 1.0, 0
	s_cselect_b32 s1, -1, 0
	s_add_i32 s1, s56, s1
	s_mul_i32 s0, s56, 0x1d00
	s_add_u32 s76, s28, s0
	s_addc_u32 s77, s29, 0
	s_mul_i32 s0, s1, 0x1d00
	s_add_u32 s78, s28, s0
	s_addc_u32 s79, s29, 0
	global_load_dwordx2 v[222:223], v250, s[76:77] offset:0
	global_load_dwordx2 v[224:225], v250, s[76:77] offset:512
	global_load_dwordx2 v[226:227], v250, s[76:77] offset:1024
	global_load_dwordx2 v[228:229], v250, s[78:79] offset:0
	global_load_dwordx2 v[230:231], v250, s[78:79] offset:512
	global_load_dwordx2 v[232:233], v250, s[78:79] offset:1024
	ds_read_b128 v[14:17], v31 offset:8192
	ds_read_b128 v[18:21], v31 offset:28672
	s_waitcnt vmcnt(19)
	v_lshlrev_b32_e32 v134, 16, v236
	v_and_b32_e32 v236, 0xffff0000, v236
	v_lshlrev_b32_e32 v135, 16, v237
	v_and_b32_e32 v237, 0xffff0000, v237
	v_lshlrev_b32_e32 v136, 16, v238
	v_and_b32_e32 v238, 0xffff0000, v238
	v_lshlrev_b32_e32 v137, 16, v239
	v_and_b32_e32 v239, 0xffff0000, v239
	v_lshlrev_b32_e32 v138, 16, v240
	v_and_b32_e32 v240, 0xffff0000, v240
	v_lshlrev_b32_e32 v139, 16, v241
	v_and_b32_e32 v241, 0xffff0000, v241
	v_lshlrev_b32_e32 v140, 16, v242
	v_and_b32_e32 v242, 0xffff0000, v242
	v_lshlrev_b32_e32 v141, 16, v243
	v_and_b32_e32 v243, 0xffff0000, v243
	v_lshlrev_b32_e32 v142, 16, v244
	v_and_b32_e32 v244, 0xffff0000, v244
	v_lshlrev_b32_e32 v143, 16, v245
	v_and_b32_e32 v245, 0xffff0000, v245
	v_lshlrev_b32_e32 v144, 16, v246
	v_and_b32_e32 v246, 0xffff0000, v246
	v_lshlrev_b32_e32 v145, 16, v247
	v_and_b32_e32 v247, 0xffff0000, v247
	v_fma_f32 v140, s60, v140, -v134
	v_fma_f32 v242, s60, v242, -v236
	v_fma_f32 v141, s60, v141, -v135
	v_fma_f32 v243, s60, v243, -v237
	v_fmac_f32_e32 v134, v210, v140
	v_fmac_f32_e32 v236, v211, v242
	v_fmac_f32_e32 v135, v212, v141
	v_fmac_f32_e32 v237, v213, v243
	v_fma_f32 v142, s60, v142, -v136
	v_fma_f32 v244, s60, v244, -v238
	v_fma_f32 v143, s60, v143, -v137
	v_fma_f32 v245, s60, v245, -v239
	v_fmac_f32_e32 v136, v214, v142
	v_fmac_f32_e32 v238, v215, v244
	v_fmac_f32_e32 v137, v216, v143
	v_fmac_f32_e32 v239, v217, v245
	v_fma_f32 v144, s60, v144, -v138
	v_fma_f32 v246, s60, v246, -v240
	v_fma_f32 v145, s60, v145, -v139
	v_fma_f32 v247, s60, v247, -v241
	v_fmac_f32_e32 v138, v218, v144
	v_fmac_f32_e32 v240, v219, v246
	v_fmac_f32_e32 v139, v220, v145
	v_fmac_f32_e32 v241, v221, v247
	v_mul_f32_e32 v148, v198, v136
	v_mul_f32_e32 v149, v199, v238
	v_mul_f32_e32 v150, v200, v137
	v_mul_f32_e32 v151, v201, v239
	v_mul_f32_e32 v176, v148, v148
	v_fmac_f32_e32 v176, v149, v149
	v_fmac_f32_e32 v176, v150, v150
	v_fmac_f32_e32 v176, v151, v151
	s_waitcnt lgkmcnt(2)
	v_fmamk_f32 v26, v26, 0xbfb8aa3b, v194
	v_fmamk_f32 v27, v27, 0xbfb8aa3b, v195
	v_fmamk_f32 v28, v28, 0xbfb8aa3b, v196
	v_fmamk_f32 v29, v29, 0xbfb8aa3b, v197
	v_add_f32_dpp v176, v176, v176 quad_perm:[1,0,3,2] row_mask:0xf bank_mask:0xf bound_ctrl:1
	v_exp_f32_e32 v26, v26
	v_exp_f32_e32 v27, v27
	v_exp_f32_e32 v28, v28
	v_exp_f32_e32 v29, v29
	v_add_f32_dpp v176, v176, v176 quad_perm:[2,3,0,1] row_mask:0xf bank_mask:0xf bound_ctrl:1
	v_add_f32_e32 v26, 1.0, v26
	v_add_f32_e32 v27, 1.0, v27
	v_add_f32_e32 v28, 1.0, v28
	v_add_f32_e32 v29, 1.0, v29
	v_add_f32_dpp v176, v176, v176 row_half_mirror row_mask:0xf bank_mask:0xf bound_ctrl:1
	v_rcp_f32_e32 v26, v26
	v_rcp_f32_e32 v27, v27
	v_rcp_f32_e32 v28, v28
	v_rcp_f32_e32 v29, v29
	v_add_f32_dpp v176, v176, v176 row_mirror row_mask:0xf bank_mask:0xf bound_ctrl:1
	v_fmamk_f32 v22, v22, 0xbfb8aa3b, v190
	v_fmamk_f32 v23, v23, 0xbfb8aa3b, v191
	v_fmamk_f32 v24, v24, 0xbfb8aa3b, v192
	v_fmamk_f32 v25, v25, 0xbfb8aa3b, v193
	v_sqrt_f32_e32 v176, v176
	v_exp_f32_e32 v22, v22
	v_exp_f32_e32 v23, v23
	v_exp_f32_e32 v24, v24
	v_exp_f32_e32 v25, v25
	v_max_f32_e32 v176, 0x2b8cbccc, v176
	v_add_f32_e32 v22, 1.0, v22
	v_add_f32_e32 v23, 1.0, v23
	v_add_f32_e32 v24, 1.0, v24
	v_add_f32_e32 v25, 1.0, v25
	v_rcp_f32_e32 v178, v176
	v_rcp_f32_e32 v22, v22
	v_rcp_f32_e32 v23, v23
	v_rcp_f32_e32 v24, v24
	v_rcp_f32_e32 v25, v25
	v_mul_f32_e32 v22, 0xbf60028a, v22
	v_mul_f32_e32 v23, 0xbf60028a, v23
	v_mul_f32_e32 v24, 0xbf60028a, v24
	v_mul_f32_e32 v25, 0xbf60028a, v25
	v_exp_f32_e32 v22, v22
	v_exp_f32_e32 v23, v23
	v_exp_f32_e32 v24, v24
	v_exp_f32_e32 v25, v25
	v_fma_f32 v152, v26, v202, v33
	v_fma_f32 v153, v27, v203, v34
	v_fma_f32 v154, v28, v204, v35
	v_fma_f32 v155, v29, v205, v36
	v_mul_f32_e32 v152, v136, v152
	v_mul_f32_e32 v153, v238, v153
	v_mul_f32_e32 v154, v137, v154
	v_mul_f32_e32 v155, v239, v155
	v_mul_f32_e32 v156, v134, v152
	v_mul_f32_e32 v157, v236, v153
	v_mul_f32_e32 v158, v135, v154
	v_mul_f32_e32 v159, v237, v155
	v_mul_f32_e32 v177, v206, v156
	v_fmac_f32_e32 v177, v207, v157
	v_fmac_f32_e32 v177, v208, v158
	v_fmac_f32_e32 v177, v209, v159
	v_mul_f32_e32 v148, v148, v178
	v_mul_f32_e32 v149, v149, v178
	v_add_f32_dpp v177, v177, v177 quad_perm:[1,0,3,2] row_mask:0xf bank_mask:0xf bound_ctrl:1
	v_mul_f32_e32 v150, v150, v178
	v_mul_f32_e32 v151, v151, v178
	v_add_f32_dpp v177, v177, v177 quad_perm:[2,3,0,1] row_mask:0xf bank_mask:0xf bound_ctrl:1
	v_mul_f32_e32 v26, v26, v148
	v_mul_f32_e32 v27, v27, v149
	v_add_f32_dpp v177, v177, v177 row_half_mirror row_mask:0xf bank_mask:0xf bound_ctrl:1
	v_mul_f32_e32 v28, v28, v150
	v_mul_f32_e32 v29, v29, v151
	v_add_f32_dpp v177, v177, v177 row_mirror row_mask:0xf bank_mask:0xf bound_ctrl:1
	s_lshl_b32 s0, s57, 9
	s_add_u32 s62, s34, s0
	s_addc_u32 s63, s35, 0
	v_mul_f32_e32 v156, v138, v177
	v_mul_f32_e32 v157, v240, v177
	v_mul_f32_e32 v158, v139, v177
	v_mul_f32_e32 v159, v241, v177
	v_cvt_pk_bf16_f32 v72, v134, v236
	v_cvt_pk_bf16_f32 v73, v135, v237
	global_store_dwordx2 v250, v[72:73], s[62:63]
	v_cvt_pk_bf16_f32 v74, v22, v23
	v_cvt_pk_bf16_f32 v75, v24, v25
	s_add_u32 s0, s62, 0x500000
	s_addc_u32 s1, s63, 0
	global_store_dwordx2 v250, v[74:75], s[0:1]
	v_cvt_pk_bf16_f32 v180, v152, v153
	v_cvt_pk_bf16_f32 v181, v154, v155
	s_add_u32 s0, s62, 0xa00000
	s_addc_u32 s1, s63, 0
	global_store_dwordx2 v250, v[180:181], s[0:1]
	v_cvt_pk_bf16_f32 v72, v138, v240
	v_cvt_pk_bf16_f32 v73, v139, v241
	s_add_u32 s0, s62, 0xf00000
	s_addc_u32 s1, s63, 0
	global_store_dwordx2 v250, v[72:73], s[0:1]
	v_cvt_pk_bf16_f32 v74, v148, v149
	v_cvt_pk_bf16_f32 v75, v150, v151
	s_add_u32 s0, s62, 0x1400000
	s_addc_u32 s1, s63, 0
	global_store_dwordx2 v250, v[74:75], s[0:1]
	v_cvt_pk_bf16_f32 v180, v26, v27
	v_cvt_pk_bf16_f32 v181, v28, v29
	s_add_u32 s0, s62, 0x1900000
	s_addc_u32 s1, s63, 0
	global_store_dwordx2 v250, v[180:181], s[0:1]
	v_cvt_pk_bf16_f32 v72, v156, v157
	v_cvt_pk_bf16_f32 v73, v158, v159
	s_lshl_b32 s0, s57, 9
	s_add_u32 s0, s42, s0
	s_addc_u32 s1, s43, 0
	global_store_dwordx2 v250, v[72:73], s[0:1]
	s_add_i32 s57, s53, 16
	s_cmpk_lt_i32 s57, 0x2000
	s_movk_i32 s0, 0x3ff
	s_cselect_b32 s0, 0xff, s0
	s_and_b32 s1, s57, s0
	s_cmp_lg_u32 s1, 0
	s_cselect_b32 s60, 1.0, 0
	s_cselect_b32 s1, -1, 0
	s_add_i32 s1, s57, s1
	s_mul_i32 s0, s57, 0x1d00
	s_add_u32 s80, s28, s0
	s_addc_u32 s81, s29, 0
	s_mul_i32 s0, s1, 0x1d00
	s_add_u32 s82, s28, s0
	s_addc_u32 s83, s29, 0
	global_load_dwordx2 v[236:237], v250, s[80:81] offset:0
	global_load_dwordx2 v[238:239], v250, s[80:81] offset:512
	global_load_dwordx2 v[240:241], v250, s[80:81] offset:1024
	global_load_dwordx2 v[242:243], v250, s[82:83] offset:0
	global_load_dwordx2 v[244:245], v250, s[82:83] offset:512
	global_load_dwordx2 v[246:247], v250, s[82:83] offset:1024
	ds_read_b128 v[22:25], v31 offset:12288
	ds_read_b128 v[26:29], v31 offset:32768
	s_waitcnt vmcnt(26)
	v_lshlrev_b32_e32 v134, 16, v0
	v_and_b32_e32 v0, 0xffff0000, v0
	v_lshlrev_b32_e32 v135, 16, v1
	v_and_b32_e32 v1, 0xffff0000, v1
	v_lshlrev_b32_e32 v136, 16, v2
	v_and_b32_e32 v2, 0xffff0000, v2
	v_lshlrev_b32_e32 v137, 16, v3
	v_and_b32_e32 v3, 0xffff0000, v3
	v_lshlrev_b32_e32 v138, 16, v4
	v_and_b32_e32 v4, 0xffff0000, v4
	v_lshlrev_b32_e32 v139, 16, v5
	v_and_b32_e32 v5, 0xffff0000, v5
	v_lshlrev_b32_e32 v140, 16, v6
	v_and_b32_e32 v6, 0xffff0000, v6
	v_lshlrev_b32_e32 v141, 16, v7
	v_and_b32_e32 v7, 0xffff0000, v7
	v_lshlrev_b32_e32 v142, 16, v8
	v_and_b32_e32 v8, 0xffff0000, v8
	v_lshlrev_b32_e32 v143, 16, v9
	v_and_b32_e32 v9, 0xffff0000, v9
	v_lshlrev_b32_e32 v144, 16, v10
	v_and_b32_e32 v10, 0xffff0000, v10
	v_lshlrev_b32_e32 v145, 16, v11
	v_and_b32_e32 v11, 0xffff0000, v11
	v_fma_f32 v140, s61, v140, -v134
	v_fma_f32 v6, s61, v6, -v0
	v_fma_f32 v141, s61, v141, -v135
	v_fma_f32 v7, s61, v7, -v1
	v_fmac_f32_e32 v134, v210, v140
	v_fmac_f32_e32 v0, v211, v6
	v_fmac_f32_e32 v135, v212, v141
	v_fmac_f32_e32 v1, v213, v7
	v_fma_f32 v142, s61, v142, -v136
	v_fma_f32 v8, s61, v8, -v2
	v_fma_f32 v143, s61, v143, -v137
	v_fma_f32 v9, s61, v9, -v3
	v_fmac_f32_e32 v136, v214, v142
	v_fmac_f32_e32 v2, v215, v8
	v_fmac_f32_e32 v137, v216, v143
	v_fmac_f32_e32 v3, v217, v9
	v_fma_f32 v144, s61, v144, -v138
	v_fma_f32 v10, s61, v10, -v4
	v_fma_f32 v145, s61, v145, -v139
	v_fma_f32 v11, s61, v11, -v5
	v_fmac_f32_e32 v138, v218, v144
	v_fmac_f32_e32 v4, v219, v10
	v_fmac_f32_e32 v139, v220, v145
	v_fmac_f32_e32 v5, v221, v11
	v_mul_f32_e32 v148, v198, v136
	v_mul_f32_e32 v149, v199, v2
	v_mul_f32_e32 v150, v200, v137
	v_mul_f32_e32 v151, v201, v3
	v_mul_f32_e32 v176, v148, v148
	v_fmac_f32_e32 v176, v149, v149
	v_fmac_f32_e32 v176, v150, v150
	v_fmac_f32_e32 v176, v151, v151
	s_waitcnt lgkmcnt(2)
	v_fmamk_f32 v18, v18, 0xbfb8aa3b, v194
	v_fmamk_f32 v19, v19, 0xbfb8aa3b, v195
	v_fmamk_f32 v20, v20, 0xbfb8aa3b, v196
	v_fmamk_f32 v21, v21, 0xbfb8aa3b, v197
	v_add_f32_dpp v176, v176, v176 quad_perm:[1,0,3,2] row_mask:0xf bank_mask:0xf bound_ctrl:1
	v_exp_f32_e32 v18, v18
	v_exp_f32_e32 v19, v19
	v_exp_f32_e32 v20, v20
	v_exp_f32_e32 v21, v21
	v_add_f32_dpp v176, v176, v176 quad_perm:[2,3,0,1] row_mask:0xf bank_mask:0xf bound_ctrl:1
	v_add_f32_e32 v18, 1.0, v18
	v_add_f32_e32 v19, 1.0, v19
	v_add_f32_e32 v20, 1.0, v20
	v_add_f32_e32 v21, 1.0, v21
	v_add_f32_dpp v176, v176, v176 row_half_mirror row_mask:0xf bank_mask:0xf bound_ctrl:1
	v_rcp_f32_e32 v18, v18
	v_rcp_f32_e32 v19, v19
	v_rcp_f32_e32 v20, v20
	v_rcp_f32_e32 v21, v21
	v_add_f32_dpp v176, v176, v176 row_mirror row_mask:0xf bank_mask:0xf bound_ctrl:1
	v_fmamk_f32 v14, v14, 0xbfb8aa3b, v190
	v_fmamk_f32 v15, v15, 0xbfb8aa3b, v191
	v_fmamk_f32 v16, v16, 0xbfb8aa3b, v192
	v_fmamk_f32 v17, v17, 0xbfb8aa3b, v193
	v_sqrt_f32_e32 v176, v176
	v_exp_f32_e32 v14, v14
	v_exp_f32_e32 v15, v15
	v_exp_f32_e32 v16, v16
	v_exp_f32_e32 v17, v17
	v_max_f32_e32 v176, 0x2b8cbccc, v176
	v_add_f32_e32 v14, 1.0, v14
	v_add_f32_e32 v15, 1.0, v15
	v_add_f32_e32 v16, 1.0, v16
	v_add_f32_e32 v17, 1.0, v17
	v_rcp_f32_e32 v178, v176
	v_rcp_f32_e32 v14, v14
	v_rcp_f32_e32 v15, v15
	v_rcp_f32_e32 v16, v16
	v_rcp_f32_e32 v17, v17
	v_mul_f32_e32 v14, 0xbf60028a, v14
	v_mul_f32_e32 v15, 0xbf60028a, v15
	v_mul_f32_e32 v16, 0xbf60028a, v16
	v_mul_f32_e32 v17, 0xbf60028a, v17
	v_exp_f32_e32 v14, v14
	v_exp_f32_e32 v15, v15
	v_exp_f32_e32 v16, v16
	v_exp_f32_e32 v17, v17
	v_fma_f32 v152, v18, v202, v33
	v_fma_f32 v153, v19, v203, v34
	v_fma_f32 v154, v20, v204, v35
	v_fma_f32 v155, v21, v205, v36
	v_mul_f32_e32 v152, v136, v152
	v_mul_f32_e32 v153, v2, v153
	v_mul_f32_e32 v154, v137, v154
	v_mul_f32_e32 v155, v3, v155
	v_mul_f32_e32 v156, v134, v152
	v_mul_f32_e32 v157, v0, v153
	v_mul_f32_e32 v158, v135, v154
	v_mul_f32_e32 v159, v1, v155
	v_mul_f32_e32 v177, v206, v156
	v_fmac_f32_e32 v177, v207, v157
	v_fmac_f32_e32 v177, v208, v158
	v_fmac_f32_e32 v177, v209, v159
	v_mul_f32_e32 v148, v148, v178
	v_mul_f32_e32 v149, v149, v178
	v_add_f32_dpp v177, v177, v177 quad_perm:[1,0,3,2] row_mask:0xf bank_mask:0xf bound_ctrl:1
	v_mul_f32_e32 v150, v150, v178
	v_mul_f32_e32 v151, v151, v178
	v_add_f32_dpp v177, v177, v177 quad_perm:[2,3,0,1] row_mask:0xf bank_mask:0xf bound_ctrl:1
	v_mul_f32_e32 v18, v18, v148
	v_mul_f32_e32 v19, v19, v149
	v_add_f32_dpp v177, v177, v177 row_half_mirror row_mask:0xf bank_mask:0xf bound_ctrl:1
	v_mul_f32_e32 v20, v20, v150
	v_mul_f32_e32 v21, v21, v151
	v_add_f32_dpp v177, v177, v177 row_mirror row_mask:0xf bank_mask:0xf bound_ctrl:1
	s_lshl_b32 s0, s58, 9
	s_add_u32 s62, s34, s0
	s_addc_u32 s63, s35, 0
	v_mul_f32_e32 v156, v138, v177
	v_mul_f32_e32 v157, v4, v177
	v_mul_f32_e32 v158, v139, v177
	v_mul_f32_e32 v159, v5, v177
	v_cvt_pk_bf16_f32 v72, v134, v0
	v_cvt_pk_bf16_f32 v73, v135, v1
	global_store_dwordx2 v250, v[72:73], s[62:63]
	v_cvt_pk_bf16_f32 v74, v14, v15
	v_cvt_pk_bf16_f32 v75, v16, v17
	s_add_u32 s0, s62, 0x500000
	s_addc_u32 s1, s63, 0
	global_store_dwordx2 v250, v[74:75], s[0:1]
	v_cvt_pk_bf16_f32 v180, v152, v153
	v_cvt_pk_bf16_f32 v181, v154, v155
	s_add_u32 s0, s62, 0xa00000
	s_addc_u32 s1, s63, 0
	global_store_dwordx2 v250, v[180:181], s[0:1]
	v_cvt_pk_bf16_f32 v72, v138, v4
	v_cvt_pk_bf16_f32 v73, v139, v5
	s_add_u32 s0, s62, 0xf00000
	s_addc_u32 s1, s63, 0
	global_store_dwordx2 v250, v[72:73], s[0:1]
	v_cvt_pk_bf16_f32 v74, v148, v149
	v_cvt_pk_bf16_f32 v75, v150, v151
	s_add_u32 s0, s62, 0x1400000
	s_addc_u32 s1, s63, 0
	global_store_dwordx2 v250, v[74:75], s[0:1]
	v_cvt_pk_bf16_f32 v180, v18, v19
	v_cvt_pk_bf16_f32 v181, v20, v21
	s_add_u32 s0, s62, 0x1900000
	s_addc_u32 s1, s63, 0
	global_store_dwordx2 v250, v[180:181], s[0:1]
	v_cvt_pk_bf16_f32 v72, v156, v157
	v_cvt_pk_bf16_f32 v73, v158, v159
	s_lshl_b32 s0, s58, 9
	s_add_u32 s0, s42, s0
	s_addc_u32 s1, s43, 0
	global_store_dwordx2 v250, v[72:73], s[0:1]
	ds_read_b128 v[14:17], v31 offset:16384
	ds_read_b128 v[18:21], v31 offset:36864
	s_waitcnt vmcnt(20)
	v_lshlrev_b32_e32 v134, 16, v222
	v_and_b32_e32 v222, 0xffff0000, v222
	v_lshlrev_b32_e32 v135, 16, v223
	v_and_b32_e32 v223, 0xffff0000, v223
	v_lshlrev_b32_e32 v136, 16, v224
	v_and_b32_e32 v224, 0xffff0000, v224
	v_lshlrev_b32_e32 v137, 16, v225
	v_and_b32_e32 v225, 0xffff0000, v225
	v_lshlrev_b32_e32 v138, 16, v226
	v_and_b32_e32 v226, 0xffff0000, v226
	v_lshlrev_b32_e32 v139, 16, v227
	v_and_b32_e32 v227, 0xffff0000, v227
	v_lshlrev_b32_e32 v140, 16, v228
	v_and_b32_e32 v228, 0xffff0000, v228
	v_lshlrev_b32_e32 v141, 16, v229
	v_and_b32_e32 v229, 0xffff0000, v229
	v_lshlrev_b32_e32 v142, 16, v230
	v_and_b32_e32 v230, 0xffff0000, v230
	v_lshlrev_b32_e32 v143, 16, v231
	v_and_b32_e32 v231, 0xffff0000, v231
	v_lshlrev_b32_e32 v144, 16, v232
	v_and_b32_e32 v232, 0xffff0000, v232
	v_lshlrev_b32_e32 v145, 16, v233
	v_and_b32_e32 v233, 0xffff0000, v233
	v_fma_f32 v140, s59, v140, -v134
	v_fma_f32 v228, s59, v228, -v222
	v_fma_f32 v141, s59, v141, -v135
	v_fma_f32 v229, s59, v229, -v223
	v_fmac_f32_e32 v134, v210, v140
	v_fmac_f32_e32 v222, v211, v228
	v_fmac_f32_e32 v135, v212, v141
	v_fmac_f32_e32 v223, v213, v229
	v_fma_f32 v142, s59, v142, -v136
	v_fma_f32 v230, s59, v230, -v224
	v_fma_f32 v143, s59, v143, -v137
	v_fma_f32 v231, s59, v231, -v225
	v_fmac_f32_e32 v136, v214, v142
	v_fmac_f32_e32 v224, v215, v230
	v_fmac_f32_e32 v137, v216, v143
	v_fmac_f32_e32 v225, v217, v231
	v_fma_f32 v144, s59, v144, -v138
	v_fma_f32 v232, s59, v232, -v226
	v_fma_f32 v145, s59, v145, -v139
	v_fma_f32 v233, s59, v233, -v227
	v_fmac_f32_e32 v138, v218, v144
	v_fmac_f32_e32 v226, v219, v232
	v_fmac_f32_e32 v139, v220, v145
	v_fmac_f32_e32 v227, v221, v233
	v_mul_f32_e32 v148, v198, v136
	v_mul_f32_e32 v149, v199, v224
	v_mul_f32_e32 v150, v200, v137
	v_mul_f32_e32 v151, v201, v225
	v_mul_f32_e32 v176, v148, v148
	v_fmac_f32_e32 v176, v149, v149
	v_fmac_f32_e32 v176, v150, v150
	v_fmac_f32_e32 v176, v151, v151
	s_waitcnt lgkmcnt(2)
	v_fmamk_f32 v26, v26, 0xbfb8aa3b, v194
	v_fmamk_f32 v27, v27, 0xbfb8aa3b, v195
	v_fmamk_f32 v28, v28, 0xbfb8aa3b, v196
	v_fmamk_f32 v29, v29, 0xbfb8aa3b, v197
	v_add_f32_dpp v176, v176, v176 quad_perm:[1,0,3,2] row_mask:0xf bank_mask:0xf bound_ctrl:1
	v_exp_f32_e32 v26, v26
	v_exp_f32_e32 v27, v27
	v_exp_f32_e32 v28, v28
	v_exp_f32_e32 v29, v29
	v_add_f32_dpp v176, v176, v176 quad_perm:[2,3,0,1] row_mask:0xf bank_mask:0xf bound_ctrl:1
	v_add_f32_e32 v26, 1.0, v26
	v_add_f32_e32 v27, 1.0, v27
	v_add_f32_e32 v28, 1.0, v28
	v_add_f32_e32 v29, 1.0, v29
	v_add_f32_dpp v176, v176, v176 row_half_mirror row_mask:0xf bank_mask:0xf bound_ctrl:1
	v_rcp_f32_e32 v26, v26
	v_rcp_f32_e32 v27, v27
	v_rcp_f32_e32 v28, v28
	v_rcp_f32_e32 v29, v29
	v_add_f32_dpp v176, v176, v176 row_mirror row_mask:0xf bank_mask:0xf bound_ctrl:1
	v_fmamk_f32 v22, v22, 0xbfb8aa3b, v190
	v_fmamk_f32 v23, v23, 0xbfb8aa3b, v191
	v_fmamk_f32 v24, v24, 0xbfb8aa3b, v192
	v_fmamk_f32 v25, v25, 0xbfb8aa3b, v193
	v_sqrt_f32_e32 v176, v176
	v_exp_f32_e32 v22, v22
	v_exp_f32_e32 v23, v23
	v_exp_f32_e32 v24, v24
	v_exp_f32_e32 v25, v25
	v_max_f32_e32 v176, 0x2b8cbccc, v176
	v_add_f32_e32 v22, 1.0, v22
	v_add_f32_e32 v23, 1.0, v23
	v_add_f32_e32 v24, 1.0, v24
	v_add_f32_e32 v25, 1.0, v25
	v_rcp_f32_e32 v178, v176
	v_rcp_f32_e32 v22, v22
	v_rcp_f32_e32 v23, v23
	v_rcp_f32_e32 v24, v24
	v_rcp_f32_e32 v25, v25
	v_mul_f32_e32 v22, 0xbf60028a, v22
	v_mul_f32_e32 v23, 0xbf60028a, v23
	v_mul_f32_e32 v24, 0xbf60028a, v24
	v_mul_f32_e32 v25, 0xbf60028a, v25
	v_exp_f32_e32 v22, v22
	v_exp_f32_e32 v23, v23
	v_exp_f32_e32 v24, v24
	v_exp_f32_e32 v25, v25
	v_fma_f32 v152, v26, v202, v33
	v_fma_f32 v153, v27, v203, v34
	v_fma_f32 v154, v28, v204, v35
	v_fma_f32 v155, v29, v205, v36
	v_mul_f32_e32 v152, v136, v152
	v_mul_f32_e32 v153, v224, v153
	v_mul_f32_e32 v154, v137, v154
	v_mul_f32_e32 v155, v225, v155
	v_mul_f32_e32 v156, v134, v152
	v_mul_f32_e32 v157, v222, v153
	v_mul_f32_e32 v158, v135, v154
	v_mul_f32_e32 v159, v223, v155
	v_mul_f32_e32 v177, v206, v156
	v_fmac_f32_e32 v177, v207, v157
	v_fmac_f32_e32 v177, v208, v158
	v_fmac_f32_e32 v177, v209, v159
	v_mul_f32_e32 v148, v148, v178
	v_mul_f32_e32 v149, v149, v178
	v_add_f32_dpp v177, v177, v177 quad_perm:[1,0,3,2] row_mask:0xf bank_mask:0xf bound_ctrl:1
	v_mul_f32_e32 v150, v150, v178
	v_mul_f32_e32 v151, v151, v178
	v_add_f32_dpp v177, v177, v177 quad_perm:[2,3,0,1] row_mask:0xf bank_mask:0xf bound_ctrl:1
	v_mul_f32_e32 v26, v26, v148
	v_mul_f32_e32 v27, v27, v149
	v_add_f32_dpp v177, v177, v177 row_half_mirror row_mask:0xf bank_mask:0xf bound_ctrl:1
	v_mul_f32_e32 v28, v28, v150
	v_mul_f32_e32 v29, v29, v151
	v_add_f32_dpp v177, v177, v177 row_mirror row_mask:0xf bank_mask:0xf bound_ctrl:1
	s_lshl_b32 s0, s56, 9
	s_add_u32 s62, s34, s0
	s_addc_u32 s63, s35, 0
	v_mul_f32_e32 v156, v138, v177
	v_mul_f32_e32 v157, v226, v177
	v_mul_f32_e32 v158, v139, v177
	v_mul_f32_e32 v159, v227, v177
	v_cvt_pk_bf16_f32 v72, v134, v222
	v_cvt_pk_bf16_f32 v73, v135, v223
	global_store_dwordx2 v250, v[72:73], s[62:63]
	v_cvt_pk_bf16_f32 v74, v22, v23
	v_cvt_pk_bf16_f32 v75, v24, v25
	s_add_u32 s0, s62, 0x500000
	s_addc_u32 s1, s63, 0
	global_store_dwordx2 v250, v[74:75], s[0:1]
	v_cvt_pk_bf16_f32 v180, v152, v153
	v_cvt_pk_bf16_f32 v181, v154, v155
	s_add_u32 s0, s62, 0xa00000
	s_addc_u32 s1, s63, 0
	global_store_dwordx2 v250, v[180:181], s[0:1]
	v_cvt_pk_bf16_f32 v72, v138, v226
	v_cvt_pk_bf16_f32 v73, v139, v227
	s_add_u32 s0, s62, 0xf00000
	s_addc_u32 s1, s63, 0
	global_store_dwordx2 v250, v[72:73], s[0:1]
	v_cvt_pk_bf16_f32 v74, v148, v149
	v_cvt_pk_bf16_f32 v75, v150, v151
	s_add_u32 s0, s62, 0x1400000
	s_addc_u32 s1, s63, 0
	global_store_dwordx2 v250, v[74:75], s[0:1]
	v_cvt_pk_bf16_f32 v180, v26, v27
	v_cvt_pk_bf16_f32 v181, v28, v29
	s_add_u32 s0, s62, 0x1900000
	s_addc_u32 s1, s63, 0
	global_store_dwordx2 v250, v[180:181], s[0:1]
	v_cvt_pk_bf16_f32 v72, v156, v157
	v_cvt_pk_bf16_f32 v73, v158, v159
	s_lshl_b32 s0, s56, 9
	s_add_u32 s0, s42, s0
	s_addc_u32 s1, s43, 0
	global_store_dwordx2 v250, v[72:73], s[0:1]
	s_waitcnt vmcnt(14)
	v_lshlrev_b32_e32 v134, 16, v236
	v_and_b32_e32 v236, 0xffff0000, v236
	v_lshlrev_b32_e32 v135, 16, v237
	v_and_b32_e32 v237, 0xffff0000, v237
	v_lshlrev_b32_e32 v136, 16, v238
	v_and_b32_e32 v238, 0xffff0000, v238
	v_lshlrev_b32_e32 v137, 16, v239
	v_and_b32_e32 v239, 0xffff0000, v239
	v_lshlrev_b32_e32 v138, 16, v240
	v_and_b32_e32 v240, 0xffff0000, v240
	v_lshlrev_b32_e32 v139, 16, v241
	v_and_b32_e32 v241, 0xffff0000, v241
	v_lshlrev_b32_e32 v140, 16, v242
	v_and_b32_e32 v242, 0xffff0000, v242
	v_lshlrev_b32_e32 v141, 16, v243
	v_and_b32_e32 v243, 0xffff0000, v243
	v_lshlrev_b32_e32 v142, 16, v244
	v_and_b32_e32 v244, 0xffff0000, v244
	v_lshlrev_b32_e32 v143, 16, v245
	v_and_b32_e32 v245, 0xffff0000, v245
	v_lshlrev_b32_e32 v144, 16, v246
	v_and_b32_e32 v246, 0xffff0000, v246
	v_lshlrev_b32_e32 v145, 16, v247
	v_and_b32_e32 v247, 0xffff0000, v247
	v_fma_f32 v140, s60, v140, -v134
	v_fma_f32 v242, s60, v242, -v236
	v_fma_f32 v141, s60, v141, -v135
	v_fma_f32 v243, s60, v243, -v237
	v_fmac_f32_e32 v134, v210, v140
	v_fmac_f32_e32 v236, v211, v242
	v_fmac_f32_e32 v135, v212, v141
	v_fmac_f32_e32 v237, v213, v243
	v_fma_f32 v142, s60, v142, -v136
	v_fma_f32 v244, s60, v244, -v238
	v_fma_f32 v143, s60, v143, -v137
	v_fma_f32 v245, s60, v245, -v239
	v_fmac_f32_e32 v136, v214, v142
	v_fmac_f32_e32 v238, v215, v244
	v_fmac_f32_e32 v137, v216, v143
	v_fmac_f32_e32 v239, v217, v245
	v_fma_f32 v144, s60, v144, -v138
	v_fma_f32 v246, s60, v246, -v240
	v_fma_f32 v145, s60, v145, -v139
	v_fma_f32 v247, s60, v247, -v241
	v_fmac_f32_e32 v138, v218, v144
	v_fmac_f32_e32 v240, v219, v246
	v_fmac_f32_e32 v139, v220, v145
	v_fmac_f32_e32 v241, v221, v247
	v_mul_f32_e32 v148, v198, v136
	v_mul_f32_e32 v149, v199, v238
	v_mul_f32_e32 v150, v200, v137
	v_mul_f32_e32 v151, v201, v239
	v_mul_f32_e32 v176, v148, v148
	v_fmac_f32_e32 v176, v149, v149
	v_fmac_f32_e32 v176, v150, v150
	v_fmac_f32_e32 v176, v151, v151
	s_waitcnt lgkmcnt(0)
	v_fmamk_f32 v18, v18, 0xbfb8aa3b, v194
	v_fmamk_f32 v19, v19, 0xbfb8aa3b, v195
	v_fmamk_f32 v20, v20, 0xbfb8aa3b, v196
	v_fmamk_f32 v21, v21, 0xbfb8aa3b, v197
	v_add_f32_dpp v176, v176, v176 quad_perm:[1,0,3,2] row_mask:0xf bank_mask:0xf bound_ctrl:1
	v_exp_f32_e32 v18, v18
	v_exp_f32_e32 v19, v19
	v_exp_f32_e32 v20, v20
	v_exp_f32_e32 v21, v21
	v_add_f32_dpp v176, v176, v176 quad_perm:[2,3,0,1] row_mask:0xf bank_mask:0xf bound_ctrl:1
	v_add_f32_e32 v18, 1.0, v18
	v_add_f32_e32 v19, 1.0, v19
	v_add_f32_e32 v20, 1.0, v20
	v_add_f32_e32 v21, 1.0, v21
	v_add_f32_dpp v176, v176, v176 row_half_mirror row_mask:0xf bank_mask:0xf bound_ctrl:1
	v_rcp_f32_e32 v18, v18
	v_rcp_f32_e32 v19, v19
	v_rcp_f32_e32 v20, v20
	v_rcp_f32_e32 v21, v21
	v_add_f32_dpp v176, v176, v176 row_mirror row_mask:0xf bank_mask:0xf bound_ctrl:1
	v_fmamk_f32 v14, v14, 0xbfb8aa3b, v190
	v_fmamk_f32 v15, v15, 0xbfb8aa3b, v191
	v_fmamk_f32 v16, v16, 0xbfb8aa3b, v192
	v_fmamk_f32 v17, v17, 0xbfb8aa3b, v193
	v_sqrt_f32_e32 v176, v176
	v_exp_f32_e32 v14, v14
	v_exp_f32_e32 v15, v15
	v_exp_f32_e32 v16, v16
	v_exp_f32_e32 v17, v17
	v_max_f32_e32 v176, 0x2b8cbccc, v176
	v_add_f32_e32 v14, 1.0, v14
	v_add_f32_e32 v15, 1.0, v15
	v_add_f32_e32 v16, 1.0, v16
	v_add_f32_e32 v17, 1.0, v17
	v_rcp_f32_e32 v178, v176
	v_rcp_f32_e32 v14, v14
	v_rcp_f32_e32 v15, v15
	v_rcp_f32_e32 v16, v16
	v_rcp_f32_e32 v17, v17
	v_mul_f32_e32 v14, 0xbf60028a, v14
	v_mul_f32_e32 v15, 0xbf60028a, v15
	v_mul_f32_e32 v16, 0xbf60028a, v16
	v_mul_f32_e32 v17, 0xbf60028a, v17
	v_exp_f32_e32 v14, v14
	v_exp_f32_e32 v15, v15
	v_exp_f32_e32 v16, v16
	v_exp_f32_e32 v17, v17
	v_fma_f32 v152, v18, v202, v33
	v_fma_f32 v153, v19, v203, v34
	v_fma_f32 v154, v20, v204, v35
	v_fma_f32 v155, v21, v205, v36
	v_mul_f32_e32 v152, v136, v152
	v_mul_f32_e32 v153, v238, v153
	v_mul_f32_e32 v154, v137, v154
	v_mul_f32_e32 v155, v239, v155
	v_mul_f32_e32 v156, v134, v152
	v_mul_f32_e32 v157, v236, v153
	v_mul_f32_e32 v158, v135, v154
	v_mul_f32_e32 v159, v237, v155
	v_mul_f32_e32 v177, v206, v156
	v_fmac_f32_e32 v177, v207, v157
	v_fmac_f32_e32 v177, v208, v158
	v_fmac_f32_e32 v177, v209, v159
	v_mul_f32_e32 v148, v148, v178
	v_mul_f32_e32 v149, v149, v178
	v_add_f32_dpp v177, v177, v177 quad_perm:[1,0,3,2] row_mask:0xf bank_mask:0xf bound_ctrl:1
	v_mul_f32_e32 v150, v150, v178
	v_mul_f32_e32 v151, v151, v178
	v_add_f32_dpp v177, v177, v177 quad_perm:[2,3,0,1] row_mask:0xf bank_mask:0xf bound_ctrl:1
	v_mul_f32_e32 v18, v18, v148
	v_mul_f32_e32 v19, v19, v149
	v_add_f32_dpp v177, v177, v177 row_half_mirror row_mask:0xf bank_mask:0xf bound_ctrl:1
	v_mul_f32_e32 v20, v20, v150
	v_mul_f32_e32 v21, v21, v151
	v_add_f32_dpp v177, v177, v177 row_mirror row_mask:0xf bank_mask:0xf bound_ctrl:1
	s_lshl_b32 s0, s57, 9
	s_add_u32 s62, s34, s0
	s_addc_u32 s63, s35, 0
	v_mul_f32_e32 v156, v138, v177
	v_mul_f32_e32 v157, v240, v177
	v_mul_f32_e32 v158, v139, v177
	v_mul_f32_e32 v159, v241, v177
	v_cvt_pk_bf16_f32 v72, v134, v236
	v_cvt_pk_bf16_f32 v73, v135, v237
	global_store_dwordx2 v250, v[72:73], s[62:63]
	v_cvt_pk_bf16_f32 v74, v14, v15
	v_cvt_pk_bf16_f32 v75, v16, v17
	s_add_u32 s0, s62, 0x500000
	s_addc_u32 s1, s63, 0
	global_store_dwordx2 v250, v[74:75], s[0:1]
	v_cvt_pk_bf16_f32 v180, v152, v153
	v_cvt_pk_bf16_f32 v181, v154, v155
	s_add_u32 s0, s62, 0xa00000
	s_addc_u32 s1, s63, 0
	global_store_dwordx2 v250, v[180:181], s[0:1]
	v_cvt_pk_bf16_f32 v72, v138, v240
	v_cvt_pk_bf16_f32 v73, v139, v241
	s_add_u32 s0, s62, 0xf00000
	s_addc_u32 s1, s63, 0
	global_store_dwordx2 v250, v[72:73], s[0:1]
	v_cvt_pk_bf16_f32 v74, v148, v149
	v_cvt_pk_bf16_f32 v75, v150, v151
	s_add_u32 s0, s62, 0x1400000
	s_addc_u32 s1, s63, 0
	global_store_dwordx2 v250, v[74:75], s[0:1]
	v_cvt_pk_bf16_f32 v180, v18, v19
	v_cvt_pk_bf16_f32 v181, v20, v21
	s_add_u32 s0, s62, 0x1900000
	s_addc_u32 s1, s63, 0
	global_store_dwordx2 v250, v[180:181], s[0:1]
	v_cvt_pk_bf16_f32 v72, v156, v157
	v_cvt_pk_bf16_f32 v73, v158, v159
	s_lshl_b32 s0, s57, 9
	s_add_u32 s0, s42, s0
	s_addc_u32 s1, s43, 0
	global_store_dwordx2 v250, v[72:73], s[0:1]
	s_branch .LBB0_476
.Lprep_tok_d1:
	ds_read_b128 v[210:213], v251 offset:53248
	ds_read_b128 v[214:217], v251 offset:54272
	ds_read_b128 v[218:221], v251 offset:55296
	ds_read_b128 v[198:201], v251 offset:56320
	ds_read_b128 v[194:197], v251 offset:57344
	ds_read_b128 v[190:193], v251 offset:58368
	ds_read_b128 v[202:205], v251 offset:59392
	ds_read_b128 v[206:209], v251 offset:60416
	s_add_u32 s34, s34, 0x1e00000
	s_addc_u32 s35, s35, 0
	s_add_i32 s56, s53, 0
	s_cmpk_lt_i32 s56, 0x2000
	s_movk_i32 s0, 0x3ff
	s_cselect_b32 s0, 0xff, s0
	s_and_b32 s1, s56, s0
	s_cmp_lg_u32 s1, s0
	s_cselect_b32 s59, 1.0, 0
	s_cselect_b32 s1, 1, 0
	s_add_i32 s1, s56, s1
	s_mul_i32 s0, s56, 0x1d00
	s_add_u32 s76, s28, s0
	s_addc_u32 s77, s29, 0
	s_mul_i32 s0, s1, 0x1d00
	s_add_u32 s78, s28, s0
	s_addc_u32 s79, s29, 0
	global_load_dwordx2 v[222:223], v250, s[76:77] offset:0
	global_load_dwordx2 v[224:225], v250, s[76:77] offset:512
	global_load_dwordx2 v[226:227], v250, s[76:77] offset:1024
	global_load_dwordx2 v[228:229], v250, s[78:79] offset:0
	global_load_dwordx2 v[230:231], v250, s[78:79] offset:512
	global_load_dwordx2 v[232:233], v250, s[78:79] offset:1024
	s_lshl_b32 s0, s56, 9
	s_add_u32 s0, s42, s0
	s_addc_u32 s1, s43, 0
	global_load_dwordx2 v[234:235], v250, s[0:1]
	s_add_i32 s57, s53, 4
	s_cmpk_lt_i32 s57, 0x2000
	s_movk_i32 s0, 0x3ff
	s_cselect_b32 s0, 0xff, s0
	s_and_b32 s1, s57, s0
	s_cmp_lg_u32 s1, s0
	s_cselect_b32 s60, 1.0, 0
	s_cselect_b32 s1, 1, 0
	s_add_i32 s1, s57, s1
	s_mul_i32 s0, s57, 0x1d00
	s_add_u32 s80, s28, s0
	s_addc_u32 s81, s29, 0
	s_mul_i32 s0, s1, 0x1d00
	s_add_u32 s82, s28, s0
	s_addc_u32 s83, s29, 0
	global_load_dwordx2 v[236:237], v250, s[80:81] offset:0
	global_load_dwordx2 v[238:239], v250, s[80:81] offset:512
	global_load_dwordx2 v[240:241], v250, s[80:81] offset:1024
	global_load_dwordx2 v[242:243], v250, s[82:83] offset:0
	global_load_dwordx2 v[244:245], v250, s[82:83] offset:512
	global_load_dwordx2 v[246:247], v250, s[82:83] offset:1024
	s_lshl_b32 s0, s57, 9
	s_add_u32 s0, s42, s0
	s_addc_u32 s1, s43, 0
	global_load_dwordx2 v[248:249], v250, s[0:1]
	s_add_i32 s58, s53, 8
	s_cmpk_lt_i32 s58, 0x2000
	s_movk_i32 s0, 0x3ff
	s_cselect_b32 s0, 0xff, s0
	s_and_b32 s1, s58, s0
	s_cmp_lg_u32 s1, s0
	s_cselect_b32 s61, 1.0, 0
	s_cselect_b32 s1, 1, 0
	s_add_i32 s1, s58, s1
	s_mul_i32 s0, s58, 0x1d00
	s_add_u32 s84, s28, s0
	s_addc_u32 s85, s29, 0
	s_mul_i32 s0, s1, 0x1d00
	s_add_u32 s96, s28, s0
	s_addc_u32 s97, s29, 0
	global_load_dwordx2 v[0:1], v250, s[84:85] offset:0
	global_load_dwordx2 v[2:3], v250, s[84:85] offset:512
	global_load_dwordx2 v[4:5], v250, s[84:85] offset:1024
	global_load_dwordx2 v[6:7], v250, s[96:97] offset:0
	global_load_dwordx2 v[8:9], v250, s[96:97] offset:512
	global_load_dwordx2 v[10:11], v250, s[96:97] offset:1024
	s_lshl_b32 s0, s58, 9
	s_add_u32 s0, s42, s0
	s_addc_u32 s1, s43, 0
	global_load_dwordx2 v[12:13], v250, s[0:1]
	ds_read_b128 v[14:17], v31 offset:0
	ds_read_b128 v[18:21], v31 offset:20480
	ds_read_b128 v[22:25], v31 offset:4096
	ds_read_b128 v[26:29], v31 offset:24576
	s_waitcnt lgkmcnt(4)
	s_waitcnt vmcnt(14)
	v_lshlrev_b32_e32 v134, 16, v222
	v_and_b32_e32 v222, 0xffff0000, v222
	v_lshlrev_b32_e32 v135, 16, v223
	v_and_b32_e32 v223, 0xffff0000, v223
	v_lshlrev_b32_e32 v136, 16, v224
	v_and_b32_e32 v224, 0xffff0000, v224
	v_lshlrev_b32_e32 v137, 16, v225
	v_and_b32_e32 v225, 0xffff0000, v225
	v_lshlrev_b32_e32 v138, 16, v226
	v_and_b32_e32 v226, 0xffff0000, v226
	v_lshlrev_b32_e32 v139, 16, v227
	v_and_b32_e32 v227, 0xffff0000, v227
	v_lshlrev_b32_e32 v140, 16, v228
	v_and_b32_e32 v228, 0xffff0000, v228
	v_lshlrev_b32_e32 v141, 16, v229
	v_and_b32_e32 v229, 0xffff0000, v229
	v_lshlrev_b32_e32 v142, 16, v230
	v_and_b32_e32 v230, 0xffff0000, v230
	v_lshlrev_b32_e32 v143, 16, v231
	v_and_b32_e32 v231, 0xffff0000, v231
	v_lshlrev_b32_e32 v144, 16, v232
	v_and_b32_e32 v232, 0xffff0000, v232
	v_lshlrev_b32_e32 v145, 16, v233
	v_and_b32_e32 v233, 0xffff0000, v233
	v_lshlrev_b32_e32 v146, 16, v234
	v_and_b32_e32 v234, 0xffff0000, v234
	v_lshlrev_b32_e32 v147, 16, v235
	v_and_b32_e32 v235, 0xffff0000, v235
	v_fma_f32 v140, s59, v140, -v134
	v_fma_f32 v228, s59, v228, -v222
	v_fma_f32 v141, s59, v141, -v135
	v_fma_f32 v229, s59, v229, -v223
	v_fmac_f32_e32 v134, v210, v140
	v_fmac_f32_e32 v222, v211, v228
	v_fmac_f32_e32 v135, v212, v141
	v_fmac_f32_e32 v223, v213, v229
	v_fma_f32 v142, s59, v142, -v136
	v_fma_f32 v230, s59, v230, -v224
	v_fma_f32 v143, s59, v143, -v137
	v_fma_f32 v231, s59, v231, -v225
	v_fmac_f32_e32 v136, v214, v142
	v_fmac_f32_e32 v224, v215, v230
	v_fmac_f32_e32 v137, v216, v143
	v_fmac_f32_e32 v225, v217, v231
	v_fma_f32 v144, s59, v144, -v138
	v_fma_f32 v232, s59, v232, -v226
	v_fma_f32 v145, s59, v145, -v139
	v_fma_f32 v233, s59, v233, -v227
	v_fmac_f32_e32 v138, v218, v144
	v_fmac_f32_e32 v226, v219, v232
	v_fmac_f32_e32 v139, v220, v145
	v_fmac_f32_e32 v227, v221, v233
	v_mul_f32_e32 v148, v198, v136
	v_mul_f32_e32 v149, v199, v224
	v_mul_f32_e32 v150, v200, v137
	v_mul_f32_e32 v151, v201, v225
	v_mul_f32_e32 v176, v148, v148
	v_fmac_f32_e32 v176, v149, v149
	v_fmac_f32_e32 v176, v150, v150
	v_fmac_f32_e32 v176, v151, v151
	s_waitcnt lgkmcnt(2)
	v_mul_f32_e32 v194, 0xbfb8aa3b, v194
	v_mul_f32_e32 v195, 0xbfb8aa3b, v195
	v_mul_f32_e32 v196, 0xbfb8aa3b, v196
	v_mul_f32_e32 v197, 0xbfb8aa3b, v197
	v_mul_f32_e32 v190, 0xbfb8aa3b, v190
	v_mul_f32_e32 v191, 0xbfb8aa3b, v191
	v_mul_f32_e32 v192, 0xbfb8aa3b, v192
	v_mul_f32_e32 v193, 0xbfb8aa3b, v193
	v_sub_f32_e32 v33, 1.0, v202
	v_sub_f32_e32 v34, 1.0, v203
	v_sub_f32_e32 v35, 1.0, v204
	v_sub_f32_e32 v36, 1.0, v205
	v_fmamk_f32 v18, v18, 0xbfb8aa3b, v194
	v_fmamk_f32 v19, v19, 0xbfb8aa3b, v195
	v_fmamk_f32 v20, v20, 0xbfb8aa3b, v196
	v_fmamk_f32 v21, v21, 0xbfb8aa3b, v197
	v_add_f32_dpp v176, v176, v176 quad_perm:[1,0,3,2] row_mask:0xf bank_mask:0xf bound_ctrl:1
	v_exp_f32_e32 v18, v18
	v_exp_f32_e32 v19, v19
	v_exp_f32_e32 v20, v20
	v_exp_f32_e32 v21, v21
	v_add_f32_dpp v176, v176, v176 quad_perm:[2,3,0,1] row_mask:0xf bank_mask:0xf bound_ctrl:1
	v_add_f32_e32 v18, 1.0, v18
	v_add_f32_e32 v19, 1.0, v19
	v_add_f32_e32 v20, 1.0, v20
	v_add_f32_e32 v21, 1.0, v21
	v_add_f32_dpp v176, v176, v176 row_half_mirror row_mask:0xf bank_mask:0xf bound_ctrl:1
	v_rcp_f32_e32 v18, v18
	v_rcp_f32_e32 v19, v19
	v_rcp_f32_e32 v20, v20
	v_rcp_f32_e32 v21, v21
	v_add_f32_dpp v176, v176, v176 row_mirror row_mask:0xf bank_mask:0xf bound_ctrl:1
	v_fmamk_f32 v14, v14, 0xbfb8aa3b, v190
	v_fmamk_f32 v15, v15, 0xbfb8aa3b, v191
	v_fmamk_f32 v16, v16, 0xbfb8aa3b, v192
	v_fmamk_f32 v17, v17, 0xbfb8aa3b, v193
	v_sqrt_f32_e32 v176, v176
	v_exp_f32_e32 v14, v14
	v_exp_f32_e32 v15, v15
	v_exp_f32_e32 v16, v16
	v_exp_f32_e32 v17, v17
	v_max_f32_e32 v176, 0x2b8cbccc, v176
	v_add_f32_e32 v14, 1.0, v14
	v_add_f32_e32 v15, 1.0, v15
	v_add_f32_e32 v16, 1.0, v16
	v_add_f32_e32 v17, 1.0, v17
	v_rcp_f32_e32 v178, v176
	v_rcp_f32_e32 v14, v14
	v_rcp_f32_e32 v15, v15
	v_rcp_f32_e32 v16, v16
	v_rcp_f32_e32 v17, v17
	v_mul_f32_e32 v14, 0xbf60028a, v14
	v_mul_f32_e32 v15, 0xbf60028a, v15
	v_mul_f32_e32 v16, 0xbf60028a, v16
	v_mul_f32_e32 v17, 0xbf60028a, v17
	v_exp_f32_e32 v14, v14
	v_exp_f32_e32 v15, v15
	v_exp_f32_e32 v16, v16
	v_exp_f32_e32 v17, v17
	v_fma_f32 v152, v18, v202, v33
	v_fma_f32 v153, v19, v203, v34
	v_fma_f32 v154, v20, v204, v35
	v_fma_f32 v155, v21, v205, v36
	v_mul_f32_e32 v152, v136, v152
	v_mul_f32_e32 v153, v224, v153
	v_mul_f32_e32 v154, v137, v154
	v_mul_f32_e32 v155, v225, v155
	v_mul_f32_e32 v156, v134, v152
	v_mul_f32_e32 v157, v222, v153
	v_mul_f32_e32 v158, v135, v154
	v_mul_f32_e32 v159, v223, v155
	v_mul_f32_e32 v177, v206, v156
	v_fmac_f32_e32 v177, v207, v157
	v_fmac_f32_e32 v177, v208, v158
	v_fmac_f32_e32 v177, v209, v159
	v_mul_f32_e32 v148, v148, v178
	v_mul_f32_e32 v149, v149, v178
	v_add_f32_dpp v177, v177, v177 quad_perm:[1,0,3,2] row_mask:0xf bank_mask:0xf bound_ctrl:1
	v_mul_f32_e32 v150, v150, v178
	v_mul_f32_e32 v151, v151, v178
	v_add_f32_dpp v177, v177, v177 quad_perm:[2,3,0,1] row_mask:0xf bank_mask:0xf bound_ctrl:1
	v_mul_f32_e32 v18, v18, v148
	v_mul_f32_e32 v19, v19, v149
	v_add_f32_dpp v177, v177, v177 row_half_mirror row_mask:0xf bank_mask:0xf bound_ctrl:1
	v_mul_f32_e32 v20, v20, v150
	v_mul_f32_e32 v21, v21, v151
	v_add_f32_dpp v177, v177, v177 row_mirror row_mask:0xf bank_mask:0xf bound_ctrl:1
	s_lshl_b32 s0, s56, 9
	s_add_u32 s62, s34, s0
	s_addc_u32 s63, s35, 0
	v_fmac_f32_e32 v146, v138, v177
	v_fmac_f32_e32 v234, v226, v177
	v_fmac_f32_e32 v147, v139, v177
	v_fmac_f32_e32 v235, v227, v177
	v_cvt_pk_bf16_f32 v72, v134, v222
	v_cvt_pk_bf16_f32 v73, v135, v223
	global_store_dwordx2 v250, v[72:73], s[62:63]
	v_cvt_pk_bf16_f32 v74, v14, v15
	v_cvt_pk_bf16_f32 v75, v16, v17
	s_add_u32 s0, s62, 0x500000
	s_addc_u32 s1, s63, 0
	global_store_dwordx2 v250, v[74:75], s[0:1]
	v_cvt_pk_bf16_f32 v180, v152, v153
	v_cvt_pk_bf16_f32 v181, v154, v155
	s_add_u32 s0, s62, 0xa00000
	s_addc_u32 s1, s63, 0
	global_store_dwordx2 v250, v[180:181], s[0:1]
	v_cvt_pk_bf16_f32 v72, v138, v226
	v_cvt_pk_bf16_f32 v73, v139, v227
	s_add_u32 s0, s62, 0xf00000
	s_addc_u32 s1, s63, 0
	global_store_dwordx2 v250, v[72:73], s[0:1]
	v_cvt_pk_bf16_f32 v74, v148, v149
	v_cvt_pk_bf16_f32 v75, v150, v151
	s_add_u32 s0, s62, 0x1400000
	s_addc_u32 s1, s63, 0
	global_store_dwordx2 v250, v[74:75], s[0:1]
	v_cvt_pk_bf16_f32 v180, v18, v19
	v_cvt_pk_bf16_f32 v181, v20, v21
	s_add_u32 s0, s62, 0x1900000
	s_addc_u32 s1, s63, 0
	global_store_dwordx2 v250, v[180:181], s[0:1]
	v_cvt_pk_bf16_f32 v72, v146, v234
	v_cvt_pk_bf16_f32 v73, v147, v235
	s_lshl_b32 s0, s56, 9
	s_add_u32 s0, s42, s0
	s_addc_u32 s1, s43, 0
	global_store_dwordx2 v250, v[72:73], s[0:1]
	s_add_i32 s56, s53, 12
	s_cmpk_lt_i32 s56, 0x2000
	s_movk_i32 s0, 0x3ff
	s_cselect_b32 s0, 0xff, s0
	s_and_b32 s1, s56, s0
	s_cmp_lg_u32 s1, s0
	s_cselect_b32 s59, 1.0, 0
	s_cselect_b32 s1, 1, 0
	s_add_i32 s1, s56, s1
	s_mul_i32 s0, s56, 0x1d00
	s_add_u32 s76, s28, s0
	s_addc_u32 s77, s29, 0
	s_mul_i32 s0, s1, 0x1d00
	s_add_u32 s78, s28, s0
	s_addc_u32 s79, s29, 0
	global_load_dwordx2 v[222:223], v250, s[76:77] offset:0
	global_load_dwordx2 v[224:225], v250, s[76:77] offset:512
	global_load_dwordx2 v[226:227], v250, s[76:77] offset:1024
	global_load_dwordx2 v[228:229], v250, s[78:79] offset:0
	global_load_dwordx2 v[230:231], v250, s[78:79] offset:512
	global_load_dwordx2 v[232:233], v250, s[78:79] offset:1024
	s_lshl_b32 s0, s56, 9
	s_add_u32 s0, s42, s0
	s_addc_u32 s1, s43, 0
	global_load_dwordx2 v[234:235], v250, s[0:1]
	ds_read_b128 v[14:17], v31 offset:8192
	ds_read_b128 v[18:21], v31 offset:28672
	s_waitcnt vmcnt(21)
	v_lshlrev_b32_e32 v134, 16, v236
	v_and_b32_e32 v236, 0xffff0000, v236
	v_lshlrev_b32_e32 v135, 16, v237
	v_and_b32_e32 v237, 0xffff0000, v237
	v_lshlrev_b32_e32 v136, 16, v238
	v_and_b32_e32 v238, 0xffff0000, v238
	v_lshlrev_b32_e32 v137, 16, v239
	v_and_b32_e32 v239, 0xffff0000, v239
	v_lshlrev_b32_e32 v138, 16, v240
	v_and_b32_e32 v240, 0xffff0000, v240
	v_lshlrev_b32_e32 v139, 16, v241
	v_and_b32_e32 v241, 0xffff0000, v241
	v_lshlrev_b32_e32 v140, 16, v242
	v_and_b32_e32 v242, 0xffff0000, v242
	v_lshlrev_b32_e32 v141, 16, v243
	v_and_b32_e32 v243, 0xffff0000, v243
	v_lshlrev_b32_e32 v142, 16, v244
	v_and_b32_e32 v244, 0xffff0000, v244
	v_lshlrev_b32_e32 v143, 16, v245
	v_and_b32_e32 v245, 0xffff0000, v245
	v_lshlrev_b32_e32 v144, 16, v246
	v_and_b32_e32 v246, 0xffff0000, v246
	v_lshlrev_b32_e32 v145, 16, v247
	v_and_b32_e32 v247, 0xffff0000, v247
	v_lshlrev_b32_e32 v146, 16, v248
	v_and_b32_e32 v248, 0xffff0000, v248
	v_lshlrev_b32_e32 v147, 16, v249
	v_and_b32_e32 v249, 0xffff0000, v249
	v_fma_f32 v140, s60, v140, -v134
	v_fma_f32 v242, s60, v242, -v236
	v_fma_f32 v141, s60, v141, -v135
	v_fma_f32 v243, s60, v243, -v237
	v_fmac_f32_e32 v134, v210, v140
	v_fmac_f32_e32 v236, v211, v242
	v_fmac_f32_e32 v135, v212, v141
	v_fmac_f32_e32 v237, v213, v243
	v_fma_f32 v142, s60, v142, -v136
	v_fma_f32 v244, s60, v244, -v238
	v_fma_f32 v143, s60, v143, -v137
	v_fma_f32 v245, s60, v245, -v239
	v_fmac_f32_e32 v136, v214, v142
	v_fmac_f32_e32 v238, v215, v244
	v_fmac_f32_e32 v137, v216, v143
	v_fmac_f32_e32 v239, v217, v245
	v_fma_f32 v144, s60, v144, -v138
	v_fma_f32 v246, s60, v246, -v240
	v_fma_f32 v145, s60, v145, -v139
	v_fma_f32 v247, s60, v247, -v241
	v_fmac_f32_e32 v138, v218, v144
	v_fmac_f32_e32 v240, v219, v246
	v_fmac_f32_e32 v139, v220, v145
	v_fmac_f32_e32 v241, v221, v247
	v_mul_f32_e32 v148, v198, v136
	v_mul_f32_e32 v149, v199, v238
	v_mul_f32_e32 v150, v200, v137
	v_mul_f32_e32 v151, v201, v239
	v_mul_f32_e32 v176, v148, v148
	v_fmac_f32_e32 v176, v149, v149
	v_fmac_f32_e32 v176, v150, v150
	v_fmac_f32_e32 v176, v151, v151
	s_waitcnt lgkmcnt(2)
	v_fmamk_f32 v26, v26, 0xbfb8aa3b, v194
	v_fmamk_f32 v27, v27, 0xbfb8aa3b, v195
	v_fmamk_f32 v28, v28, 0xbfb8aa3b, v196
	v_fmamk_f32 v29, v29, 0xbfb8aa3b, v197
	v_add_f32_dpp v176, v176, v176 quad_perm:[1,0,3,2] row_mask:0xf bank_mask:0xf bound_ctrl:1
	v_exp_f32_e32 v26, v26
	v_exp_f32_e32 v27, v27
	v_exp_f32_e32 v28, v28
	v_exp_f32_e32 v29, v29
	v_add_f32_dpp v176, v176, v176 quad_perm:[2,3,0,1] row_mask:0xf bank_mask:0xf bound_ctrl:1
	v_add_f32_e32 v26, 1.0, v26
	v_add_f32_e32 v27, 1.0, v27
	v_add_f32_e32 v28, 1.0, v28
	v_add_f32_e32 v29, 1.0, v29
	v_add_f32_dpp v176, v176, v176 row_half_mirror row_mask:0xf bank_mask:0xf bound_ctrl:1
	v_rcp_f32_e32 v26, v26
	v_rcp_f32_e32 v27, v27
	v_rcp_f32_e32 v28, v28
	v_rcp_f32_e32 v29, v29
	v_add_f32_dpp v176, v176, v176 row_mirror row_mask:0xf bank_mask:0xf bound_ctrl:1
	v_fmamk_f32 v22, v22, 0xbfb8aa3b, v190
	v_fmamk_f32 v23, v23, 0xbfb8aa3b, v191
	v_fmamk_f32 v24, v24, 0xbfb8aa3b, v192
	v_fmamk_f32 v25, v25, 0xbfb8aa3b, v193
	v_sqrt_f32_e32 v176, v176
	v_exp_f32_e32 v22, v22
	v_exp_f32_e32 v23, v23
	v_exp_f32_e32 v24, v24
	v_exp_f32_e32 v25, v25
	v_max_f32_e32 v176, 0x2b8cbccc, v176
	v_add_f32_e32 v22, 1.0, v22
	v_add_f32_e32 v23, 1.0, v23
	v_add_f32_e32 v24, 1.0, v24
	v_add_f32_e32 v25, 1.0, v25
	v_rcp_f32_e32 v178, v176
	v_rcp_f32_e32 v22, v22
	v_rcp_f32_e32 v23, v23
	v_rcp_f32_e32 v24, v24
	v_rcp_f32_e32 v25, v25
	v_mul_f32_e32 v22, 0xbf60028a, v22
	v_mul_f32_e32 v23, 0xbf60028a, v23
	v_mul_f32_e32 v24, 0xbf60028a, v24
	v_mul_f32_e32 v25, 0xbf60028a, v25
	v_exp_f32_e32 v22, v22
	v_exp_f32_e32 v23, v23
	v_exp_f32_e32 v24, v24
	v_exp_f32_e32 v25, v25
	v_fma_f32 v152, v26, v202, v33
	v_fma_f32 v153, v27, v203, v34
	v_fma_f32 v154, v28, v204, v35
	v_fma_f32 v155, v29, v205, v36
	v_mul_f32_e32 v152, v136, v152
	v_mul_f32_e32 v153, v238, v153
	v_mul_f32_e32 v154, v137, v154
	v_mul_f32_e32 v155, v239, v155
	v_mul_f32_e32 v156, v134, v152
	v_mul_f32_e32 v157, v236, v153
	v_mul_f32_e32 v158, v135, v154
	v_mul_f32_e32 v159, v237, v155
	v_mul_f32_e32 v177, v206, v156
	v_fmac_f32_e32 v177, v207, v157
	v_fmac_f32_e32 v177, v208, v158
	v_fmac_f32_e32 v177, v209, v159
	v_mul_f32_e32 v148, v148, v178
	v_mul_f32_e32 v149, v149, v178
	v_add_f32_dpp v177, v177, v177 quad_perm:[1,0,3,2] row_mask:0xf bank_mask:0xf bound_ctrl:1
	v_mul_f32_e32 v150, v150, v178
	v_mul_f32_e32 v151, v151, v178
	v_add_f32_dpp v177, v177, v177 quad_perm:[2,3,0,1] row_mask:0xf bank_mask:0xf bound_ctrl:1
	v_mul_f32_e32 v26, v26, v148
	v_mul_f32_e32 v27, v27, v149
	v_add_f32_dpp v177, v177, v177 row_half_mirror row_mask:0xf bank_mask:0xf bound_ctrl:1
	v_mul_f32_e32 v28, v28, v150
	v_mul_f32_e32 v29, v29, v151
	v_add_f32_dpp v177, v177, v177 row_mirror row_mask:0xf bank_mask:0xf bound_ctrl:1
	s_lshl_b32 s0, s57, 9
	s_add_u32 s62, s34, s0
	s_addc_u32 s63, s35, 0
	v_fmac_f32_e32 v146, v138, v177
	v_fmac_f32_e32 v248, v240, v177
	v_fmac_f32_e32 v147, v139, v177
	v_fmac_f32_e32 v249, v241, v177
	v_cvt_pk_bf16_f32 v72, v134, v236
	v_cvt_pk_bf16_f32 v73, v135, v237
	global_store_dwordx2 v250, v[72:73], s[62:63]
	v_cvt_pk_bf16_f32 v74, v22, v23
	v_cvt_pk_bf16_f32 v75, v24, v25
	s_add_u32 s0, s62, 0x500000
	s_addc_u32 s1, s63, 0
	global_store_dwordx2 v250, v[74:75], s[0:1]
	v_cvt_pk_bf16_f32 v180, v152, v153
	v_cvt_pk_bf16_f32 v181, v154, v155
	s_add_u32 s0, s62, 0xa00000
	s_addc_u32 s1, s63, 0
	global_store_dwordx2 v250, v[180:181], s[0:1]
	v_cvt_pk_bf16_f32 v72, v138, v240
	v_cvt_pk_bf16_f32 v73, v139, v241
	s_add_u32 s0, s62, 0xf00000
	s_addc_u32 s1, s63, 0
	global_store_dwordx2 v250, v[72:73], s[0:1]
	v_cvt_pk_bf16_f32 v74, v148, v149
	v_cvt_pk_bf16_f32 v75, v150, v151
	s_add_u32 s0, s62, 0x1400000
	s_addc_u32 s1, s63, 0
	global_store_dwordx2 v250, v[74:75], s[0:1]
	v_cvt_pk_bf16_f32 v180, v26, v27
	v_cvt_pk_bf16_f32 v181, v28, v29
	s_add_u32 s0, s62, 0x1900000
	s_addc_u32 s1, s63, 0
	global_store_dwordx2 v250, v[180:181], s[0:1]
	v_cvt_pk_bf16_f32 v72, v146, v248
	v_cvt_pk_bf16_f32 v73, v147, v249
	s_lshl_b32 s0, s57, 9
	s_add_u32 s0, s42, s0
	s_addc_u32 s1, s43, 0
	global_store_dwordx2 v250, v[72:73], s[0:1]
	s_add_i32 s57, s53, 16
	s_cmpk_lt_i32 s57, 0x2000
	s_movk_i32 s0, 0x3ff
	s_cselect_b32 s0, 0xff, s0
	s_and_b32 s1, s57, s0
	s_cmp_lg_u32 s1, s0
	s_cselect_b32 s60, 1.0, 0
	s_cselect_b32 s1, 1, 0
	s_add_i32 s1, s57, s1
	s_mul_i32 s0, s57, 0x1d00
	s_add_u32 s80, s28, s0
	s_addc_u32 s81, s29, 0
	s_mul_i32 s0, s1, 0x1d00
	s_add_u32 s82, s28, s0
	s_addc_u32 s83, s29, 0
	global_load_dwordx2 v[236:237], v250, s[80:81] offset:0
	global_load_dwordx2 v[238:239], v250, s[80:81] offset:512
	global_load_dwordx2 v[240:241], v250, s[80:81] offset:1024
	global_load_dwordx2 v[242:243], v250, s[82:83] offset:0
	global_load_dwordx2 v[244:245], v250, s[82:83] offset:512
	global_load_dwordx2 v[246:247], v250, s[82:83] offset:1024
	s_lshl_b32 s0, s57, 9
	s_add_u32 s0, s42, s0
	s_addc_u32 s1, s43, 0
	global_load_dwordx2 v[248:249], v250, s[0:1]
	ds_read_b128 v[22:25], v31 offset:12288
	ds_read_b128 v[26:29], v31 offset:32768
	s_waitcnt vmcnt(28)
	v_lshlrev_b32_e32 v134, 16, v0
	v_and_b32_e32 v0, 0xffff0000, v0
	v_lshlrev_b32_e32 v135, 16, v1
	v_and_b32_e32 v1, 0xffff0000, v1
	v_lshlrev_b32_e32 v136, 16, v2
	v_and_b32_e32 v2, 0xffff0000, v2
	v_lshlrev_b32_e32 v137, 16, v3
	v_and_b32_e32 v3, 0xffff0000, v3
	v_lshlrev_b32_e32 v138, 16, v4
	v_and_b32_e32 v4, 0xffff0000, v4
	v_lshlrev_b32_e32 v139, 16, v5
	v_and_b32_e32 v5, 0xffff0000, v5
	v_lshlrev_b32_e32 v140, 16, v6
	v_and_b32_e32 v6, 0xffff0000, v6
	v_lshlrev_b32_e32 v141, 16, v7
	v_and_b32_e32 v7, 0xffff0000, v7
	v_lshlrev_b32_e32 v142, 16, v8
	v_and_b32_e32 v8, 0xffff0000, v8
	v_lshlrev_b32_e32 v143, 16, v9
	v_and_b32_e32 v9, 0xffff0000, v9
	v_lshlrev_b32_e32 v144, 16, v10
	v_and_b32_e32 v10, 0xffff0000, v10
	v_lshlrev_b32_e32 v145, 16, v11
	v_and_b32_e32 v11, 0xffff0000, v11
	v_lshlrev_b32_e32 v146, 16, v12
	v_and_b32_e32 v12, 0xffff0000, v12
	v_lshlrev_b32_e32 v147, 16, v13
	v_and_b32_e32 v13, 0xffff0000, v13
	v_fma_f32 v140, s61, v140, -v134
	v_fma_f32 v6, s61, v6, -v0
	v_fma_f32 v141, s61, v141, -v135
	v_fma_f32 v7, s61, v7, -v1
	v_fmac_f32_e32 v134, v210, v140
	v_fmac_f32_e32 v0, v211, v6
	v_fmac_f32_e32 v135, v212, v141
	v_fmac_f32_e32 v1, v213, v7
	v_fma_f32 v142, s61, v142, -v136
	v_fma_f32 v8, s61, v8, -v2
	v_fma_f32 v143, s61, v143, -v137
	v_fma_f32 v9, s61, v9, -v3
	v_fmac_f32_e32 v136, v214, v142
	v_fmac_f32_e32 v2, v215, v8
	v_fmac_f32_e32 v137, v216, v143
	v_fmac_f32_e32 v3, v217, v9
	v_fma_f32 v144, s61, v144, -v138
	v_fma_f32 v10, s61, v10, -v4
	v_fma_f32 v145, s61, v145, -v139
	v_fma_f32 v11, s61, v11, -v5
	v_fmac_f32_e32 v138, v218, v144
	v_fmac_f32_e32 v4, v219, v10
	v_fmac_f32_e32 v139, v220, v145
	v_fmac_f32_e32 v5, v221, v11
	v_mul_f32_e32 v148, v198, v136
	v_mul_f32_e32 v149, v199, v2
	v_mul_f32_e32 v150, v200, v137
	v_mul_f32_e32 v151, v201, v3
	v_mul_f32_e32 v176, v148, v148
	v_fmac_f32_e32 v176, v149, v149
	v_fmac_f32_e32 v176, v150, v150
	v_fmac_f32_e32 v176, v151, v151
	s_waitcnt lgkmcnt(2)
	v_fmamk_f32 v18, v18, 0xbfb8aa3b, v194
	v_fmamk_f32 v19, v19, 0xbfb8aa3b, v195
	v_fmamk_f32 v20, v20, 0xbfb8aa3b, v196
	v_fmamk_f32 v21, v21, 0xbfb8aa3b, v197
	v_add_f32_dpp v176, v176, v176 quad_perm:[1,0,3,2] row_mask:0xf bank_mask:0xf bound_ctrl:1
	v_exp_f32_e32 v18, v18
	v_exp_f32_e32 v19, v19
	v_exp_f32_e32 v20, v20
	v_exp_f32_e32 v21, v21
	v_add_f32_dpp v176, v176, v176 quad_perm:[2,3,0,1] row_mask:0xf bank_mask:0xf bound_ctrl:1
	v_add_f32_e32 v18, 1.0, v18
	v_add_f32_e32 v19, 1.0, v19
	v_add_f32_e32 v20, 1.0, v20
	v_add_f32_e32 v21, 1.0, v21
	v_add_f32_dpp v176, v176, v176 row_half_mirror row_mask:0xf bank_mask:0xf bound_ctrl:1
	v_rcp_f32_e32 v18, v18
	v_rcp_f32_e32 v19, v19
	v_rcp_f32_e32 v20, v20
	v_rcp_f32_e32 v21, v21
	v_add_f32_dpp v176, v176, v176 row_mirror row_mask:0xf bank_mask:0xf bound_ctrl:1
	v_fmamk_f32 v14, v14, 0xbfb8aa3b, v190
	v_fmamk_f32 v15, v15, 0xbfb8aa3b, v191
	v_fmamk_f32 v16, v16, 0xbfb8aa3b, v192
	v_fmamk_f32 v17, v17, 0xbfb8aa3b, v193
	v_sqrt_f32_e32 v176, v176
	v_exp_f32_e32 v14, v14
	v_exp_f32_e32 v15, v15
	v_exp_f32_e32 v16, v16
	v_exp_f32_e32 v17, v17
	v_max_f32_e32 v176, 0x2b8cbccc, v176
	v_add_f32_e32 v14, 1.0, v14
	v_add_f32_e32 v15, 1.0, v15
	v_add_f32_e32 v16, 1.0, v16
	v_add_f32_e32 v17, 1.0, v17
	v_rcp_f32_e32 v178, v176
	v_rcp_f32_e32 v14, v14
	v_rcp_f32_e32 v15, v15
	v_rcp_f32_e32 v16, v16
	v_rcp_f32_e32 v17, v17
	v_mul_f32_e32 v14, 0xbf60028a, v14
	v_mul_f32_e32 v15, 0xbf60028a, v15
	v_mul_f32_e32 v16, 0xbf60028a, v16
	v_mul_f32_e32 v17, 0xbf60028a, v17
	v_exp_f32_e32 v14, v14
	v_exp_f32_e32 v15, v15
	v_exp_f32_e32 v16, v16
	v_exp_f32_e32 v17, v17
	v_fma_f32 v152, v18, v202, v33
	v_fma_f32 v153, v19, v203, v34
	v_fma_f32 v154, v20, v204, v35
	v_fma_f32 v155, v21, v205, v36
	v_mul_f32_e32 v152, v136, v152
	v_mul_f32_e32 v153, v2, v153
	v_mul_f32_e32 v154, v137, v154
	v_mul_f32_e32 v155, v3, v155
	v_mul_f32_e32 v156, v134, v152
	v_mul_f32_e32 v157, v0, v153
	v_mul_f32_e32 v158, v135, v154
	v_mul_f32_e32 v159, v1, v155
	v_mul_f32_e32 v177, v206, v156
	v_fmac_f32_e32 v177, v207, v157
	v_fmac_f32_e32 v177, v208, v158
	v_fmac_f32_e32 v177, v209, v159
	v_mul_f32_e32 v148, v148, v178
	v_mul_f32_e32 v149, v149, v178
	v_add_f32_dpp v177, v177, v177 quad_perm:[1,0,3,2] row_mask:0xf bank_mask:0xf bound_ctrl:1
	v_mul_f32_e32 v150, v150, v178
	v_mul_f32_e32 v151, v151, v178
	v_add_f32_dpp v177, v177, v177 quad_perm:[2,3,0,1] row_mask:0xf bank_mask:0xf bound_ctrl:1
	v_mul_f32_e32 v18, v18, v148
	v_mul_f32_e32 v19, v19, v149
	v_add_f32_dpp v177, v177, v177 row_half_mirror row_mask:0xf bank_mask:0xf bound_ctrl:1
	v_mul_f32_e32 v20, v20, v150
	v_mul_f32_e32 v21, v21, v151
	v_add_f32_dpp v177, v177, v177 row_mirror row_mask:0xf bank_mask:0xf bound_ctrl:1
	s_lshl_b32 s0, s58, 9
	s_add_u32 s62, s34, s0
	s_addc_u32 s63, s35, 0
	v_fmac_f32_e32 v146, v138, v177
	v_fmac_f32_e32 v12, v4, v177
	v_fmac_f32_e32 v147, v139, v177
	v_fmac_f32_e32 v13, v5, v177
	v_cvt_pk_bf16_f32 v72, v134, v0
	v_cvt_pk_bf16_f32 v73, v135, v1
	global_store_dwordx2 v250, v[72:73], s[62:63]
	v_cvt_pk_bf16_f32 v74, v14, v15
	v_cvt_pk_bf16_f32 v75, v16, v17
	s_add_u32 s0, s62, 0x500000
	s_addc_u32 s1, s63, 0
	global_store_dwordx2 v250, v[74:75], s[0:1]
	v_cvt_pk_bf16_f32 v180, v152, v153
	v_cvt_pk_bf16_f32 v181, v154, v155
	s_add_u32 s0, s62, 0xa00000
	s_addc_u32 s1, s63, 0
	global_store_dwordx2 v250, v[180:181], s[0:1]
	v_cvt_pk_bf16_f32 v72, v138, v4
	v_cvt_pk_bf16_f32 v73, v139, v5
	s_add_u32 s0, s62, 0xf00000
	s_addc_u32 s1, s63, 0
	global_store_dwordx2 v250, v[72:73], s[0:1]
	v_cvt_pk_bf16_f32 v74, v148, v149
	v_cvt_pk_bf16_f32 v75, v150, v151
	s_add_u32 s0, s62, 0x1400000
	s_addc_u32 s1, s63, 0
	global_store_dwordx2 v250, v[74:75], s[0:1]
	v_cvt_pk_bf16_f32 v180, v18, v19
	v_cvt_pk_bf16_f32 v181, v20, v21
	s_add_u32 s0, s62, 0x1900000
	s_addc_u32 s1, s63, 0
	global_store_dwordx2 v250, v[180:181], s[0:1]
	v_cvt_pk_bf16_f32 v72, v146, v12
	v_cvt_pk_bf16_f32 v73, v147, v13
	s_lshl_b32 s0, s58, 9
	s_add_u32 s0, s42, s0
	s_addc_u32 s1, s43, 0
	global_store_dwordx2 v250, v[72:73], s[0:1]
	ds_read_b128 v[14:17], v31 offset:16384
	ds_read_b128 v[18:21], v31 offset:36864
	s_waitcnt vmcnt(21)
	v_lshlrev_b32_e32 v134, 16, v222
	v_and_b32_e32 v222, 0xffff0000, v222
	v_lshlrev_b32_e32 v135, 16, v223
	v_and_b32_e32 v223, 0xffff0000, v223
	v_lshlrev_b32_e32 v136, 16, v224
	v_and_b32_e32 v224, 0xffff0000, v224
	v_lshlrev_b32_e32 v137, 16, v225
	v_and_b32_e32 v225, 0xffff0000, v225
	v_lshlrev_b32_e32 v138, 16, v226
	v_and_b32_e32 v226, 0xffff0000, v226
	v_lshlrev_b32_e32 v139, 16, v227
	v_and_b32_e32 v227, 0xffff0000, v227
	v_lshlrev_b32_e32 v140, 16, v228
	v_and_b32_e32 v228, 0xffff0000, v228
	v_lshlrev_b32_e32 v141, 16, v229
	v_and_b32_e32 v229, 0xffff0000, v229
	v_lshlrev_b32_e32 v142, 16, v230
	v_and_b32_e32 v230, 0xffff0000, v230
	v_lshlrev_b32_e32 v143, 16, v231
	v_and_b32_e32 v231, 0xffff0000, v231
	v_lshlrev_b32_e32 v144, 16, v232
	v_and_b32_e32 v232, 0xffff0000, v232
	v_lshlrev_b32_e32 v145, 16, v233
	v_and_b32_e32 v233, 0xffff0000, v233
	v_lshlrev_b32_e32 v146, 16, v234
	v_and_b32_e32 v234, 0xffff0000, v234
	v_lshlrev_b32_e32 v147, 16, v235
	v_and_b32_e32 v235, 0xffff0000, v235
	v_fma_f32 v140, s59, v140, -v134
	v_fma_f32 v228, s59, v228, -v222
	v_fma_f32 v141, s59, v141, -v135
	v_fma_f32 v229, s59, v229, -v223
	v_fmac_f32_e32 v134, v210, v140
	v_fmac_f32_e32 v222, v211, v228
	v_fmac_f32_e32 v135, v212, v141
	v_fmac_f32_e32 v223, v213, v229
	v_fma_f32 v142, s59, v142, -v136
	v_fma_f32 v230, s59, v230, -v224
	v_fma_f32 v143, s59, v143, -v137
	v_fma_f32 v231, s59, v231, -v225
	v_fmac_f32_e32 v136, v214, v142
	v_fmac_f32_e32 v224, v215, v230
	v_fmac_f32_e32 v137, v216, v143
	v_fmac_f32_e32 v225, v217, v231
	v_fma_f32 v144, s59, v144, -v138
	v_fma_f32 v232, s59, v232, -v226
	v_fma_f32 v145, s59, v145, -v139
	v_fma_f32 v233, s59, v233, -v227
	v_fmac_f32_e32 v138, v218, v144
	v_fmac_f32_e32 v226, v219, v232
	v_fmac_f32_e32 v139, v220, v145
	v_fmac_f32_e32 v227, v221, v233
	v_mul_f32_e32 v148, v198, v136
	v_mul_f32_e32 v149, v199, v224
	v_mul_f32_e32 v150, v200, v137
	v_mul_f32_e32 v151, v201, v225
	v_mul_f32_e32 v176, v148, v148
	v_fmac_f32_e32 v176, v149, v149
	v_fmac_f32_e32 v176, v150, v150
	v_fmac_f32_e32 v176, v151, v151
	s_waitcnt lgkmcnt(2)
	v_fmamk_f32 v26, v26, 0xbfb8aa3b, v194
	v_fmamk_f32 v27, v27, 0xbfb8aa3b, v195
	v_fmamk_f32 v28, v28, 0xbfb8aa3b, v196
	v_fmamk_f32 v29, v29, 0xbfb8aa3b, v197
	v_add_f32_dpp v176, v176, v176 quad_perm:[1,0,3,2] row_mask:0xf bank_mask:0xf bound_ctrl:1
	v_exp_f32_e32 v26, v26
	v_exp_f32_e32 v27, v27
	v_exp_f32_e32 v28, v28
	v_exp_f32_e32 v29, v29
	v_add_f32_dpp v176, v176, v176 quad_perm:[2,3,0,1] row_mask:0xf bank_mask:0xf bound_ctrl:1
	v_add_f32_e32 v26, 1.0, v26
	v_add_f32_e32 v27, 1.0, v27
	v_add_f32_e32 v28, 1.0, v28
	v_add_f32_e32 v29, 1.0, v29
	v_add_f32_dpp v176, v176, v176 row_half_mirror row_mask:0xf bank_mask:0xf bound_ctrl:1
	v_rcp_f32_e32 v26, v26
	v_rcp_f32_e32 v27, v27
	v_rcp_f32_e32 v28, v28
	v_rcp_f32_e32 v29, v29
	v_add_f32_dpp v176, v176, v176 row_mirror row_mask:0xf bank_mask:0xf bound_ctrl:1
	v_fmamk_f32 v22, v22, 0xbfb8aa3b, v190
	v_fmamk_f32 v23, v23, 0xbfb8aa3b, v191
	v_fmamk_f32 v24, v24, 0xbfb8aa3b, v192
	v_fmamk_f32 v25, v25, 0xbfb8aa3b, v193
	v_sqrt_f32_e32 v176, v176
	v_exp_f32_e32 v22, v22
	v_exp_f32_e32 v23, v23
	v_exp_f32_e32 v24, v24
	v_exp_f32_e32 v25, v25
	v_max_f32_e32 v176, 0x2b8cbccc, v176
	v_add_f32_e32 v22, 1.0, v22
	v_add_f32_e32 v23, 1.0, v23
	v_add_f32_e32 v24, 1.0, v24
	v_add_f32_e32 v25, 1.0, v25
	v_rcp_f32_e32 v178, v176
	v_rcp_f32_e32 v22, v22
	v_rcp_f32_e32 v23, v23
	v_rcp_f32_e32 v24, v24
	v_rcp_f32_e32 v25, v25
	v_mul_f32_e32 v22, 0xbf60028a, v22
	v_mul_f32_e32 v23, 0xbf60028a, v23
	v_mul_f32_e32 v24, 0xbf60028a, v24
	v_mul_f32_e32 v25, 0xbf60028a, v25
	v_exp_f32_e32 v22, v22
	v_exp_f32_e32 v23, v23
	v_exp_f32_e32 v24, v24
	v_exp_f32_e32 v25, v25
	v_fma_f32 v152, v26, v202, v33
	v_fma_f32 v153, v27, v203, v34
	v_fma_f32 v154, v28, v204, v35
	v_fma_f32 v155, v29, v205, v36
	v_mul_f32_e32 v152, v136, v152
	v_mul_f32_e32 v153, v224, v153
	v_mul_f32_e32 v154, v137, v154
	v_mul_f32_e32 v155, v225, v155
	v_mul_f32_e32 v156, v134, v152
	v_mul_f32_e32 v157, v222, v153
	v_mul_f32_e32 v158, v135, v154
	v_mul_f32_e32 v159, v223, v155
	v_mul_f32_e32 v177, v206, v156
	v_fmac_f32_e32 v177, v207, v157
	v_fmac_f32_e32 v177, v208, v158
	v_fmac_f32_e32 v177, v209, v159
	v_mul_f32_e32 v148, v148, v178
	v_mul_f32_e32 v149, v149, v178
	v_add_f32_dpp v177, v177, v177 quad_perm:[1,0,3,2] row_mask:0xf bank_mask:0xf bound_ctrl:1
	v_mul_f32_e32 v150, v150, v178
	v_mul_f32_e32 v151, v151, v178
	v_add_f32_dpp v177, v177, v177 quad_perm:[2,3,0,1] row_mask:0xf bank_mask:0xf bound_ctrl:1
	v_mul_f32_e32 v26, v26, v148
	v_mul_f32_e32 v27, v27, v149
	v_add_f32_dpp v177, v177, v177 row_half_mirror row_mask:0xf bank_mask:0xf bound_ctrl:1
	v_mul_f32_e32 v28, v28, v150
	v_mul_f32_e32 v29, v29, v151
	v_add_f32_dpp v177, v177, v177 row_mirror row_mask:0xf bank_mask:0xf bound_ctrl:1
	s_lshl_b32 s0, s56, 9
	s_add_u32 s62, s34, s0
	s_addc_u32 s63, s35, 0
	v_fmac_f32_e32 v146, v138, v177
	v_fmac_f32_e32 v234, v226, v177
	v_fmac_f32_e32 v147, v139, v177
	v_fmac_f32_e32 v235, v227, v177
	v_cvt_pk_bf16_f32 v72, v134, v222
	v_cvt_pk_bf16_f32 v73, v135, v223
	global_store_dwordx2 v250, v[72:73], s[62:63]
	v_cvt_pk_bf16_f32 v74, v22, v23
	v_cvt_pk_bf16_f32 v75, v24, v25
	s_add_u32 s0, s62, 0x500000
	s_addc_u32 s1, s63, 0
	global_store_dwordx2 v250, v[74:75], s[0:1]
	v_cvt_pk_bf16_f32 v180, v152, v153
	v_cvt_pk_bf16_f32 v181, v154, v155
	s_add_u32 s0, s62, 0xa00000
	s_addc_u32 s1, s63, 0
	global_store_dwordx2 v250, v[180:181], s[0:1]
	v_cvt_pk_bf16_f32 v72, v138, v226
	v_cvt_pk_bf16_f32 v73, v139, v227
	s_add_u32 s0, s62, 0xf00000
	s_addc_u32 s1, s63, 0
	global_store_dwordx2 v250, v[72:73], s[0:1]
	v_cvt_pk_bf16_f32 v74, v148, v149
	v_cvt_pk_bf16_f32 v75, v150, v151
	s_add_u32 s0, s62, 0x1400000
	s_addc_u32 s1, s63, 0
	global_store_dwordx2 v250, v[74:75], s[0:1]
	v_cvt_pk_bf16_f32 v180, v26, v27
	v_cvt_pk_bf16_f32 v181, v28, v29
	s_add_u32 s0, s62, 0x1900000
	s_addc_u32 s1, s63, 0
	global_store_dwordx2 v250, v[180:181], s[0:1]
	v_cvt_pk_bf16_f32 v72, v146, v234
	v_cvt_pk_bf16_f32 v73, v147, v235
	s_lshl_b32 s0, s56, 9
	s_add_u32 s0, s42, s0
	s_addc_u32 s1, s43, 0
	global_store_dwordx2 v250, v[72:73], s[0:1]
	s_waitcnt vmcnt(14)
	v_lshlrev_b32_e32 v134, 16, v236
	v_and_b32_e32 v236, 0xffff0000, v236
	v_lshlrev_b32_e32 v135, 16, v237
	v_and_b32_e32 v237, 0xffff0000, v237
	v_lshlrev_b32_e32 v136, 16, v238
	v_and_b32_e32 v238, 0xffff0000, v238
	v_lshlrev_b32_e32 v137, 16, v239
	v_and_b32_e32 v239, 0xffff0000, v239
	v_lshlrev_b32_e32 v138, 16, v240
	v_and_b32_e32 v240, 0xffff0000, v240
	v_lshlrev_b32_e32 v139, 16, v241
	v_and_b32_e32 v241, 0xffff0000, v241
	v_lshlrev_b32_e32 v140, 16, v242
	v_and_b32_e32 v242, 0xffff0000, v242
	v_lshlrev_b32_e32 v141, 16, v243
	v_and_b32_e32 v243, 0xffff0000, v243
	v_lshlrev_b32_e32 v142, 16, v244
	v_and_b32_e32 v244, 0xffff0000, v244
	v_lshlrev_b32_e32 v143, 16, v245
	v_and_b32_e32 v245, 0xffff0000, v245
	v_lshlrev_b32_e32 v144, 16, v246
	v_and_b32_e32 v246, 0xffff0000, v246
	v_lshlrev_b32_e32 v145, 16, v247
	v_and_b32_e32 v247, 0xffff0000, v247
	v_lshlrev_b32_e32 v146, 16, v248
	v_and_b32_e32 v248, 0xffff0000, v248
	v_lshlrev_b32_e32 v147, 16, v249
	v_and_b32_e32 v249, 0xffff0000, v249
	v_fma_f32 v140, s60, v140, -v134
	v_fma_f32 v242, s60, v242, -v236
	v_fma_f32 v141, s60, v141, -v135
	v_fma_f32 v243, s60, v243, -v237
	v_fmac_f32_e32 v134, v210, v140
	v_fmac_f32_e32 v236, v211, v242
	v_fmac_f32_e32 v135, v212, v141
	v_fmac_f32_e32 v237, v213, v243
	v_fma_f32 v142, s60, v142, -v136
	v_fma_f32 v244, s60, v244, -v238
	v_fma_f32 v143, s60, v143, -v137
	v_fma_f32 v245, s60, v245, -v239
	v_fmac_f32_e32 v136, v214, v142
	v_fmac_f32_e32 v238, v215, v244
	v_fmac_f32_e32 v137, v216, v143
	v_fmac_f32_e32 v239, v217, v245
	v_fma_f32 v144, s60, v144, -v138
	v_fma_f32 v246, s60, v246, -v240
	v_fma_f32 v145, s60, v145, -v139
	v_fma_f32 v247, s60, v247, -v241
	v_fmac_f32_e32 v138, v218, v144
	v_fmac_f32_e32 v240, v219, v246
	v_fmac_f32_e32 v139, v220, v145
	v_fmac_f32_e32 v241, v221, v247
	v_mul_f32_e32 v148, v198, v136
	v_mul_f32_e32 v149, v199, v238
	v_mul_f32_e32 v150, v200, v137
	v_mul_f32_e32 v151, v201, v239
	v_mul_f32_e32 v176, v148, v148
	v_fmac_f32_e32 v176, v149, v149
	v_fmac_f32_e32 v176, v150, v150
	v_fmac_f32_e32 v176, v151, v151
	s_waitcnt lgkmcnt(0)
	v_fmamk_f32 v18, v18, 0xbfb8aa3b, v194
	v_fmamk_f32 v19, v19, 0xbfb8aa3b, v195
	v_fmamk_f32 v20, v20, 0xbfb8aa3b, v196
	v_fmamk_f32 v21, v21, 0xbfb8aa3b, v197
	v_add_f32_dpp v176, v176, v176 quad_perm:[1,0,3,2] row_mask:0xf bank_mask:0xf bound_ctrl:1
	v_exp_f32_e32 v18, v18
	v_exp_f32_e32 v19, v19
	v_exp_f32_e32 v20, v20
	v_exp_f32_e32 v21, v21
	v_add_f32_dpp v176, v176, v176 quad_perm:[2,3,0,1] row_mask:0xf bank_mask:0xf bound_ctrl:1
	v_add_f32_e32 v18, 1.0, v18
	v_add_f32_e32 v19, 1.0, v19
	v_add_f32_e32 v20, 1.0, v20
	v_add_f32_e32 v21, 1.0, v21
	v_add_f32_dpp v176, v176, v176 row_half_mirror row_mask:0xf bank_mask:0xf bound_ctrl:1
	v_rcp_f32_e32 v18, v18
	v_rcp_f32_e32 v19, v19
	v_rcp_f32_e32 v20, v20
	v_rcp_f32_e32 v21, v21
	v_add_f32_dpp v176, v176, v176 row_mirror row_mask:0xf bank_mask:0xf bound_ctrl:1
	v_fmamk_f32 v14, v14, 0xbfb8aa3b, v190
	v_fmamk_f32 v15, v15, 0xbfb8aa3b, v191
	v_fmamk_f32 v16, v16, 0xbfb8aa3b, v192
	v_fmamk_f32 v17, v17, 0xbfb8aa3b, v193
	v_sqrt_f32_e32 v176, v176
	v_exp_f32_e32 v14, v14
	v_exp_f32_e32 v15, v15
	v_exp_f32_e32 v16, v16
	v_exp_f32_e32 v17, v17
	v_max_f32_e32 v176, 0x2b8cbccc, v176
	v_add_f32_e32 v14, 1.0, v14
	v_add_f32_e32 v15, 1.0, v15
	v_add_f32_e32 v16, 1.0, v16
	v_add_f32_e32 v17, 1.0, v17
	v_rcp_f32_e32 v178, v176
	v_rcp_f32_e32 v14, v14
	v_rcp_f32_e32 v15, v15
	v_rcp_f32_e32 v16, v16
	v_rcp_f32_e32 v17, v17
	v_mul_f32_e32 v14, 0xbf60028a, v14
	v_mul_f32_e32 v15, 0xbf60028a, v15
	v_mul_f32_e32 v16, 0xbf60028a, v16
	v_mul_f32_e32 v17, 0xbf60028a, v17
	v_exp_f32_e32 v14, v14
	v_exp_f32_e32 v15, v15
	v_exp_f32_e32 v16, v16
	v_exp_f32_e32 v17, v17
	v_fma_f32 v152, v18, v202, v33
	v_fma_f32 v153, v19, v203, v34
	v_fma_f32 v154, v20, v204, v35
	v_fma_f32 v155, v21, v205, v36
	v_mul_f32_e32 v152, v136, v152
	v_mul_f32_e32 v153, v238, v153
	v_mul_f32_e32 v154, v137, v154
	v_mul_f32_e32 v155, v239, v155
	v_mul_f32_e32 v156, v134, v152
	v_mul_f32_e32 v157, v236, v153
	v_mul_f32_e32 v158, v135, v154
	v_mul_f32_e32 v159, v237, v155
	v_mul_f32_e32 v177, v206, v156
	v_fmac_f32_e32 v177, v207, v157
	v_fmac_f32_e32 v177, v208, v158
	v_fmac_f32_e32 v177, v209, v159
	v_mul_f32_e32 v148, v148, v178
	v_mul_f32_e32 v149, v149, v178
	v_add_f32_dpp v177, v177, v177 quad_perm:[1,0,3,2] row_mask:0xf bank_mask:0xf bound_ctrl:1
	v_mul_f32_e32 v150, v150, v178
	v_mul_f32_e32 v151, v151, v178
	v_add_f32_dpp v177, v177, v177 quad_perm:[2,3,0,1] row_mask:0xf bank_mask:0xf bound_ctrl:1
	v_mul_f32_e32 v18, v18, v148
	v_mul_f32_e32 v19, v19, v149
	v_add_f32_dpp v177, v177, v177 row_half_mirror row_mask:0xf bank_mask:0xf bound_ctrl:1
	v_mul_f32_e32 v20, v20, v150
	v_mul_f32_e32 v21, v21, v151
	v_add_f32_dpp v177, v177, v177 row_mirror row_mask:0xf bank_mask:0xf bound_ctrl:1
	s_lshl_b32 s0, s57, 9
	s_add_u32 s62, s34, s0
	s_addc_u32 s63, s35, 0
	v_fmac_f32_e32 v146, v138, v177
	v_fmac_f32_e32 v248, v240, v177
	v_fmac_f32_e32 v147, v139, v177
	v_fmac_f32_e32 v249, v241, v177
	v_cvt_pk_bf16_f32 v72, v134, v236
	v_cvt_pk_bf16_f32 v73, v135, v237
	global_store_dwordx2 v250, v[72:73], s[62:63]
	v_cvt_pk_bf16_f32 v74, v14, v15
	v_cvt_pk_bf16_f32 v75, v16, v17
	s_add_u32 s0, s62, 0x500000
	s_addc_u32 s1, s63, 0
	global_store_dwordx2 v250, v[74:75], s[0:1]
	v_cvt_pk_bf16_f32 v180, v152, v153
	v_cvt_pk_bf16_f32 v181, v154, v155
	s_add_u32 s0, s62, 0xa00000
	s_addc_u32 s1, s63, 0
	global_store_dwordx2 v250, v[180:181], s[0:1]
	v_cvt_pk_bf16_f32 v72, v138, v240
	v_cvt_pk_bf16_f32 v73, v139, v241
	s_add_u32 s0, s62, 0xf00000
	s_addc_u32 s1, s63, 0
	global_store_dwordx2 v250, v[72:73], s[0:1]
	v_cvt_pk_bf16_f32 v74, v148, v149
	v_cvt_pk_bf16_f32 v75, v150, v151
	s_add_u32 s0, s62, 0x1400000
	s_addc_u32 s1, s63, 0
	global_store_dwordx2 v250, v[74:75], s[0:1]
	v_cvt_pk_bf16_f32 v180, v18, v19
	v_cvt_pk_bf16_f32 v181, v20, v21
	s_add_u32 s0, s62, 0x1900000
	s_addc_u32 s1, s63, 0
	global_store_dwordx2 v250, v[180:181], s[0:1]
	v_cvt_pk_bf16_f32 v72, v146, v248
	v_cvt_pk_bf16_f32 v73, v147, v249
	s_lshl_b32 s0, s57, 9
	s_add_u32 s0, s42, s0
	s_addc_u32 s1, s43, 0
	global_store_dwordx2 v250, v[72:73], s[0:1]
	s_branch .LBB0_476
